# scan: a unit's conv history and first raw rows are fetched by the previous unit's last sub-block (no load wait at unit start); conv weights reloaded only when the lru block changes
# speedup vs baseline: 1.0028x; 1.0028x over previous
.LBB0_240:
	s_andn2_b64 vcc, exec, s[4:5]
	v_readlane_b32 s4, v254, 28
	v_readlane_b32 s5, v254, 29
	s_nop 1
	v_cndmask_b32_e64 v0, 0, 1, s[4:5]
	v_cmp_ne_u32_e64 s[4:5], 1, v0
	s_cbranch_vccnz .LBB0_392
	v_readlane_b32 s6, v254, 0
	v_readlane_b32 s7, v254, 1
	s_load_dwordx4 s[16:19], s[6:7], 0xb8
	v_mov_b32_e32 v85, v192
	s_mov_b32 s68, s20
	s_and_b64 vcc, exec, s[4:5]
	v_readfirstlane_b32 s0, v85
	s_cbranch_vccnz .LBB0_366
	s_waitcnt lgkmcnt(0)
	s_mov_b32 s20, s68
	s_load_dwordx4 s[8:11], s[6:7], 0x18
	s_load_dwordx2 s[12:13], s[6:7], 0x30
	s_load_dwordx4 s[24:27], s[6:7], 0x40
	v_readfirstlane_b32 s21, v192
	s_lshr_b32 s21, s21, 6
	s_add_u32 s28, s18, 0x8f29000
	s_addc_u32 s29, s19, 0
	s_add_u32 s30, s16, 0x37a8000
	s_addc_u32 s31, s17, 0
	v_and_b32_e32 v238, 63, v192
	v_and_b32_e32 v239, 15, v192
	v_bfe_u32 v240, v192, 4, 2
	s_mul_i32 s0, s21, 0x2600
	s_add_i32 s0, s0, 0xa080
	v_lshl_add_u32 v226, v238, 3, s0
	v_lshl_add_u32 v227, v238, 2, s0
	v_add_u32_e32 v227, 0x1900, v227
	v_mul_u32_u24_e32 v229, 0xd0, v239
	v_lshl_add_u32 v229, v240, 4, v229
	v_add_u32_e32 v228, s0, v229
	v_add_u32_e32 v228, 0x1900, v228
	v_lshlrev_b32_e32 v237, 4, v240
	v_add_u32_e32 v230, 0x9c00, v237
	v_mul_u32_u24_e32 v231, 0x190, v239
	v_add3_u32 v231, v231, v237, s0
	v_and_or_b32 v232, v238, 48, 15
	v_lshlrev_b32_e32 v232, 2, v232
	v_min_u32_e32 v241, 47, v238
	v_lshlrev_b32_e32 v233, 2, v241
	v_lshlrev_b32_e32 v234, 3, v241
	v_mul_u32_u24_e32 v235, 0x1800, v239
	v_lshl_add_u32 v235, v240, 3, v235
	v_mul_u32_u24_e32 v236, 0xc00, v239
	v_lshl_add_u32 v236, v240, 3, v236
	s_waitcnt lgkmcnt(0)
	s_mul_i32 s0, s20, 0x6000
	s_add_u32 s8, s8, s0
	s_addc_u32 s9, s9, 0
	s_mul_i32 s0, s20, 0x1800
	s_add_u32 s10, s10, s0
	s_addc_u32 s11, s11, 0
	s_add_u32 s12, s12, s0
	s_addc_u32 s13, s13, 0
	s_add_u32 s24, s24, s0
	s_addc_u32 s25, s25, 0
	s_add_u32 s26, s26, s0
	s_addc_u32 s27, s27, 0
	s_mov_b32 s38, -1
	s_mov_b32 s23, s2
	s_cmpk_lt_u32 s23, 0x2b0
	s_cbranch_scc0 .Lscan1_unit_test
	s_lshr_b32 s0, s23, 4
	s_lshl_b32 s0, s0, 3
	s_add_i32 s0, s0, s21
	s_mul_i32 s39, s0, 0x5f5
	s_lshr_b32 s39, s39, 16
	s_mul_i32 s62, s39, 43
	s_sub_i32 s0, s0, s62
	s_mul_i32 s39, s39, 0x810
	s_mul_i32 s0, s0, 48
	s_add_i32 s39, s39, s0
	s_mul_i32 s44, s39, 0x1800
	s_mul_hi_u32 s45, s39, 0x1800
	s_and_b32 s0, s23, 15
	s_mul_i32 s0, s0, 0xc0
	s_add_i32 s0, s0, 0xc00
	s_add_u32 s44, s44, s0
	s_addc_u32 s45, s45, 0
	s_add_u32 s44, s44, s28
	s_addc_u32 s45, s45, s29
	s_add_u32 s62, s44, 0xffffb800
	s_addc_u32 s63, s45, -1
	global_load_dword v222, v233, s[62:63]
	s_add_u32 s62, s62, 0x1800
	s_addc_u32 s63, s63, 0
	global_load_dword v223, v233, s[62:63]
	s_add_u32 s62, s62, 0x1800
	s_addc_u32 s63, s63, 0
	global_load_dword v224, v233, s[62:63]
	s_mov_b64 s[62:63], s[44:45]
	global_load_dword v66, v233, s[62:63]
	s_add_u32 s62, s62, 0x1800
	s_addc_u32 s63, s63, 0
	global_load_dword v67, v233, s[62:63]
	s_add_u32 s62, s62, 0x1800
	s_addc_u32 s63, s63, 0
	global_load_dword v68, v233, s[62:63]
	s_add_u32 s62, s62, 0x1800
	s_addc_u32 s63, s63, 0
	global_load_dword v69, v233, s[62:63]
	s_add_u32 s62, s62, 0x1800
	s_addc_u32 s63, s63, 0
	global_load_dword v70, v233, s[62:63]
	s_add_u32 s62, s62, 0x1800
	s_addc_u32 s63, s63, 0
	global_load_dword v71, v233, s[62:63]
	s_add_u32 s62, s62, 0x1800
	s_addc_u32 s63, s63, 0
	global_load_dword v72, v233, s[62:63]
	s_add_u32 s62, s62, 0x1800
	s_addc_u32 s63, s63, 0
	global_load_dword v73, v233, s[62:63]
	s_add_u32 s62, s62, 0x1800
	s_addc_u32 s63, s63, 0
	global_load_dword v74, v233, s[62:63]
	s_add_u32 s62, s62, 0x1800
	s_addc_u32 s63, s63, 0
	global_load_dword v75, v233, s[62:63]
	s_add_u32 s62, s62, 0x1800
	s_addc_u32 s63, s63, 0
	global_load_dword v76, v233, s[62:63]
	s_add_u32 s62, s62, 0x1800
	s_addc_u32 s63, s63, 0
	global_load_dword v77, v233, s[62:63]
	s_add_u32 s62, s62, 0x1800
	s_addc_u32 s63, s63, 0
	global_load_dword v78, v233, s[62:63]
	s_add_u32 s62, s62, 0x1800
	s_addc_u32 s63, s63, 0
	global_load_dword v79, v233, s[62:63]
	s_add_u32 s62, s62, 0x1800
	s_addc_u32 s63, s63, 0
	global_load_dword v80, v233, s[62:63]
	s_add_u32 s62, s62, 0x1800
	s_addc_u32 s63, s63, 0
	global_load_dword v81, v233, s[62:63]
	s_add_u32 s62, s62, 0x1800
	s_addc_u32 s63, s63, 0
	s_mov_b64 s[44:45], s[62:63]
	s_branch .Lscan1_unit_test
.Lscan1_unit:
	s_and_b32 s37, s23, 15
	s_lshr_b32 s0, s23, 4
	s_lshl_b32 s0, s0, 3
	s_add_i32 s0, s0, s21
	s_mul_i32 s55, s0, 0x5f5
	s_lshr_b32 s55, s55, 16
	s_mul_i32 s56, s55, 43
	s_sub_i32 s56, s0, s56
	s_mul_i32 s57, s55, 0x810
	s_mul_i32 s39, s56, 48
	s_add_i32 s57, s57, s39
	s_add_i32 s0, s23, s42
	s_cmpk_lt_u32 s0, 0x2b0
	s_cselect_b32 s0, s0, s23
	s_lshr_b32 s39, s0, 4
	s_lshl_b32 s39, s39, 3
	s_add_i32 s39, s39, s21
	s_mul_i32 s62, s39, 0x5f5
	s_lshr_b32 s62, s62, 16
	s_mul_i32 s63, s62, 43
	s_sub_i32 s39, s39, s63
	s_mul_i32 s62, s62, 0x810
	s_mul_i32 s39, s39, 48
	s_add_i32 s62, s62, s39
	s_mul_i32 s100, s62, 0x1800
	s_mul_hi_u32 s101, s62, 0x1800
	s_and_b32 s39, s0, 15
	s_mul_i32 s39, s39, 0xc0
	s_add_i32 s39, s39, 0xc00
	s_add_u32 s100, s100, s39
	s_addc_u32 s101, s101, 0
	s_add_u32 s100, s100, s28
	s_addc_u32 s101, s101, s29
	s_mul_i32 s39, s55, 43
	s_add_i32 s39, s39, s56
	s_mul_i32 s39, s39, 0x1800
	s_mul_i32 s0, s37, 0x180
	s_add_i32 s39, s39, s0
	s_add_u32 s62, s30, s39
	s_addc_u32 s63, s31, 0
	v_mov_b32_e32 v0, 0
	v_mov_b32_e32 v24, 1.0
	v_mov_b32_e32 v1, 0
	v_mov_b32_e32 v25, 1.0
	v_mov_b32_e32 v2, 0
	v_mov_b32_e32 v26, 1.0
	v_mov_b32_e32 v3, 0
	v_mov_b32_e32 v27, 1.0
	v_mov_b32_e32 v4, 0
	v_mov_b32_e32 v28, 1.0
	v_mov_b32_e32 v5, 0
	v_mov_b32_e32 v29, 1.0
	v_mov_b32_e32 v6, 0
	v_mov_b32_e32 v30, 1.0
	v_mov_b32_e32 v7, 0
	v_mov_b32_e32 v31, 1.0
	v_mov_b32_e32 v8, 0
	v_mov_b32_e32 v32, 1.0
	v_mov_b32_e32 v9, 0
	v_mov_b32_e32 v33, 1.0
	v_mov_b32_e32 v10, 0
	v_mov_b32_e32 v34, 1.0
	v_mov_b32_e32 v11, 0
	v_mov_b32_e32 v35, 1.0
	v_mov_b32_e32 v12, 0
	v_mov_b32_e32 v36, 1.0
	v_mov_b32_e32 v13, 0
	v_mov_b32_e32 v37, 1.0
	v_mov_b32_e32 v14, 0
	v_mov_b32_e32 v38, 1.0
	v_mov_b32_e32 v15, 0
	v_mov_b32_e32 v39, 1.0
	v_mov_b32_e32 v16, 0
	v_mov_b32_e32 v40, 1.0
	v_mov_b32_e32 v17, 0
	v_mov_b32_e32 v41, 1.0
	v_mov_b32_e32 v18, 0
	v_mov_b32_e32 v42, 1.0
	v_mov_b32_e32 v19, 0
	v_mov_b32_e32 v43, 1.0
	v_mov_b32_e32 v20, 0
	v_mov_b32_e32 v44, 1.0
	v_mov_b32_e32 v21, 0
	v_mov_b32_e32 v45, 1.0
	v_mov_b32_e32 v22, 0
	v_mov_b32_e32 v46, 1.0
	v_mov_b32_e32 v23, 0
	v_mov_b32_e32 v47, 1.0
	s_mov_b64 s[6:7], s[62:63]
	s_cmp_eq_u32 s37, s38
	s_cbranch_scc1 .Lscan1_staged
	s_mul_i32 s39, s37, 0x180
	s_add_u32 s62, s8, s39
	s_addc_u32 s63, s9, 0
	global_load_dwordx2 v[48:49], v234, s[62:63]
	s_add_u32 s62, s62, 0x1800
	s_addc_u32 s63, s63, 0
	global_load_dwordx2 v[50:51], v234, s[62:63]
	s_add_u32 s62, s62, 0x1800
	s_addc_u32 s63, s63, 0
	global_load_dwordx2 v[52:53], v234, s[62:63]
	s_add_u32 s62, s62, 0x1800
	s_addc_u32 s63, s63, 0
	global_load_dwordx2 v[54:55], v234, s[62:63]
	s_add_u32 s62, s10, s39
	s_addc_u32 s63, s11, 0
	global_load_dwordx2 v[56:57], v234, s[62:63]
	s_lshl_b32 s0, s20, 4
	s_add_i32 s0, s0, s37
	s_mul_i32 s0, s0, 0x4800
	s_add_u32 s62, s16, 0x3688000
	s_addc_u32 s63, s17, 0
	s_add_u32 s62, s62, s0
	s_addc_u32 s63, s63, 0
	v_add_u32_e32 v239, 0, v192
	v_mul_u32_u24_e32 v240, 0xaaab, v239
	v_lshrrev_b32_e32 v240, 19, v240
	v_mul_u32_u24_e32 v241, 12, v240
	v_sub_u32_e32 v241, v239, v241
	v_lshlrev_b32_e32 v241, 4, v241
	v_mul_u32_u24_e32 v118, 0xd0, v240
	v_add_u32_e32 v118, v118, v241
	v_mul_u32_u24_e32 v243, 0xc0, v240
	v_add_u32_e32 v243, v243, v241
	v_cmp_lt_u32_e32 vcc, 95, v240
	s_nop 1
	v_mov_b32_e32 v244, 0x8b800
	v_cndmask_b32_e32 v244, 0, v244, vcc
	v_add_u32_e32 v243, v243, v244
	global_load_dwordx4 v[98:101], v243, s[62:63]
	v_add_u32_e32 v239, 512, v192
	v_mul_u32_u24_e32 v240, 0xaaab, v239
	v_lshrrev_b32_e32 v240, 19, v240
	v_mul_u32_u24_e32 v241, 12, v240
	v_sub_u32_e32 v241, v239, v241
	v_lshlrev_b32_e32 v241, 4, v241
	v_mul_u32_u24_e32 v119, 0xd0, v240
	v_add_u32_e32 v119, v119, v241
	v_mul_u32_u24_e32 v243, 0xc0, v240
	v_add_u32_e32 v243, v243, v241
	v_cmp_lt_u32_e32 vcc, 95, v240
	s_nop 1
	v_mov_b32_e32 v244, 0x8b800
	v_cndmask_b32_e32 v244, 0, v244, vcc
	v_add_u32_e32 v243, v243, v244
	global_load_dwordx4 v[102:105], v243, s[62:63]
	v_add_u32_e32 v239, 1024, v192
	v_mul_u32_u24_e32 v240, 0xaaab, v239
	v_lshrrev_b32_e32 v240, 19, v240
	v_mul_u32_u24_e32 v241, 12, v240
	v_sub_u32_e32 v241, v239, v241
	v_lshlrev_b32_e32 v241, 4, v241
	v_mul_u32_u24_e32 v120, 0xd0, v240
	v_add_u32_e32 v120, v120, v241
	v_mul_u32_u24_e32 v243, 0xc0, v240
	v_add_u32_e32 v243, v243, v241
	v_cmp_lt_u32_e32 vcc, 95, v240
	s_nop 1
	v_mov_b32_e32 v244, 0x8b800
	v_cndmask_b32_e32 v244, 0, v244, vcc
	v_add_u32_e32 v243, v243, v244
	global_load_dwordx4 v[106:109], v243, s[62:63]
	v_add_u32_e32 v239, 1536, v192
	v_mul_u32_u24_e32 v240, 0xaaab, v239
	v_lshrrev_b32_e32 v240, 19, v240
	v_mul_u32_u24_e32 v241, 12, v240
	v_sub_u32_e32 v241, v239, v241
	v_lshlrev_b32_e32 v241, 4, v241
	v_mul_u32_u24_e32 v121, 0xd0, v240
	v_add_u32_e32 v121, v121, v241
	v_mul_u32_u24_e32 v243, 0xc0, v240
	v_add_u32_e32 v243, v243, v241
	v_cmp_lt_u32_e32 vcc, 95, v240
	s_nop 1
	v_mov_b32_e32 v244, 0x8b800
	v_cndmask_b32_e32 v244, 0, v244, vcc
	v_add_u32_e32 v243, v243, v244
	global_load_dwordx4 v[110:113], v243, s[62:63]
	v_add_u32_e32 v239, 2048, v192
	v_mul_u32_u24_e32 v240, 0xaaab, v239
	v_lshrrev_b32_e32 v240, 19, v240
	v_mul_u32_u24_e32 v241, 12, v240
	v_sub_u32_e32 v241, v239, v241
	v_lshlrev_b32_e32 v241, 4, v241
	v_mul_u32_u24_e32 v122, 0xd0, v240
	v_add_u32_e32 v122, v122, v241
	v_mul_u32_u24_e32 v243, 0xc0, v240
	v_add_u32_e32 v243, v243, v241
	v_cmp_lt_u32_e32 vcc, 95, v240
	s_nop 1
	v_mov_b32_e32 v244, 0x8b800
	v_cndmask_b32_e32 v244, 0, v244, vcc
	v_add_u32_e32 v243, v243, v244
	v_cmp_gt_u32_e32 vcc, 0x900, v239
	s_and_b64 exec, exec, vcc
	global_load_dwordx4 v[114:117], v243, s[62:63]
	s_mov_b64 exec, -1
	v_cmp_gt_u32_e32 vcc, 0x60, v192
	s_and_b64 exec, exec, vcc
	s_mul_i32 s0, s37, 0x180
	v_lshl_add_u32 v239, v192, 2, s0
	global_load_dword v123, v239, s[12:13]
	global_load_dword v124, v239, s[24:25]
	global_load_dword v125, v239, s[26:27]
	s_mov_b64 exec, -1
	s_waitcnt lgkmcnt(0)
	s_barrier
	s_waitcnt vmcnt(0)
	ds_write_b128 v118, v[98:101]
	ds_write_b128 v119, v[102:105]
	ds_write_b128 v120, v[106:109]
	ds_write_b128 v121, v[110:113]
	v_cmp_gt_u32_e32 vcc, 0x100, v192
	s_and_b64 exec, exec, vcc
	ds_write_b128 v122, v[114:117]
	s_mov_b64 exec, -1
	v_cmp_gt_u32_e32 vcc, 0x60, v192
	s_and_b64 exec, exec, vcc
	v_lshlrev_b32_e32 v240, 2, v192
	v_mul_f32_e32 v123, 0xbfb8aa3b, v123
	v_mul_f32_e32 v124, 0xbfb8aa3b, v124
	ds_write_b32 v240, v123 offset:39936
	ds_write_b32 v240, v124 offset:40320
	v_mul_f32_e32 v244, 0xbfb8aa3b, v125
	v_exp_f32_e32 v244, v244
	s_nop 0
	v_add_f32_e32 v245, 1.0, v244
	v_log_f32_e32 v245, v245
	v_fmamk_f32 v246, v244, 0xbe800000, v194
	v_fma_f32 v246, -v244, v246, 0.5
	v_fma_f32 v246, -v244, v246, 1.0
	v_mul_f32_e32 v246, v244, v246
	v_mul_f32_e32 v247, 0x3f317217, v245
	v_fma_f32 v247, v245, s76, -v247
	v_fmac_f32_e32 v247, 0x3377d1cf, v245
	v_fmac_f32_e32 v247, 0x3f317217, v245
	v_cmp_ngt_f32_e32 vcc, s90, v244
	s_nop 1
	v_cndmask_b32_e32 v246, v246, v247, vcc
	v_mul_f32_e32 v246, 0xc138aa3b, v246
	ds_write_b32 v240, v246 offset:40704
	s_mov_b64 exec, -1
	s_mov_b32 s38, s37
	s_waitcnt lgkmcnt(0)
	s_barrier
.Lscan1_staged:
	s_mov_b32 s66, 0xbfb8aa3b
	s_mov_b32 s67, 0xbd2ec3ff
	v_mov_b32_e32 v248, 0xbe1d955b
	v_mov_b32_e32 v249, 0xbee35847
	v_mov_b32_e32 v250, 0xbf75fdf0
	v_mov_b32_e32 v251, 0xbfb17218
	s_cmp_eq_u32 s56, 0
	s_cbranch_scc1 .Lscan1_hzero
	v_lshlrev_b32_e32 v58, 16, v222
	v_and_b32_e32 v59, 0xffff0000, v222
	v_lshlrev_b32_e32 v60, 16, v223
	v_and_b32_e32 v61, 0xffff0000, v223
	v_lshlrev_b32_e32 v62, 16, v224
	v_and_b32_e32 v63, 0xffff0000, v224
	s_branch .Lscan1_hdone

.Lscan1_sub:
	s_cmp_eq_u32 s64, 2
	s_cselect_b32 s44, s100, s44
	s_cselect_b32 s45, s101, s45
	s_add_u32 s62, s44, 0xffffb800
	s_addc_u32 s63, s45, -1
	global_load_dword v222, v233, s[62:63]
	s_add_u32 s62, s62, 0x1800
	s_addc_u32 s63, s63, 0
	global_load_dword v223, v233, s[62:63]
	s_add_u32 s62, s62, 0x1800
	s_addc_u32 s63, s63, 0
	global_load_dword v224, v233, s[62:63]
	s_mov_b64 s[62:63], s[44:45]
	global_load_dword v82, v233, s[62:63]
	s_add_u32 s62, s62, 0x1800
	s_addc_u32 s63, s63, 0
	global_load_dword v83, v233, s[62:63]
	s_add_u32 s62, s62, 0x1800
	s_addc_u32 s63, s63, 0
	global_load_dword v84, v233, s[62:63]
	s_add_u32 s62, s62, 0x1800
	s_addc_u32 s63, s63, 0
	global_load_dword v85, v233, s[62:63]
	s_add_u32 s62, s62, 0x1800
	s_addc_u32 s63, s63, 0
	global_load_dword v86, v233, s[62:63]
	s_add_u32 s62, s62, 0x1800
	s_addc_u32 s63, s63, 0
	global_load_dword v87, v233, s[62:63]
	s_add_u32 s62, s62, 0x1800
	s_addc_u32 s63, s63, 0
	global_load_dword v88, v233, s[62:63]
	s_add_u32 s62, s62, 0x1800
	s_addc_u32 s63, s63, 0
	global_load_dword v89, v233, s[62:63]
	s_add_u32 s62, s62, 0x1800
	s_addc_u32 s63, s63, 0
	global_load_dword v90, v233, s[62:63]
	s_add_u32 s62, s62, 0x1800
	s_addc_u32 s63, s63, 0
	global_load_dword v91, v233, s[62:63]
	s_add_u32 s62, s62, 0x1800
	s_addc_u32 s63, s63, 0
	global_load_dword v92, v233, s[62:63]
	s_add_u32 s62, s62, 0x1800
	s_addc_u32 s63, s63, 0
	global_load_dword v93, v233, s[62:63]
	s_add_u32 s62, s62, 0x1800
	s_addc_u32 s63, s63, 0
	global_load_dword v94, v233, s[62:63]
	s_add_u32 s62, s62, 0x1800
	s_addc_u32 s63, s63, 0
	global_load_dword v95, v233, s[62:63]
	s_add_u32 s62, s62, 0x1800
	s_addc_u32 s63, s63, 0
	global_load_dword v96, v233, s[62:63]
	s_add_u32 s62, s62, 0x1800
	s_addc_u32 s63, s63, 0
	global_load_dword v97, v233, s[62:63]
	s_add_u32 s62, s62, 0x1800
	s_addc_u32 s63, s63, 0
	s_mov_b64 s[44:45], s[62:63]
	ds_read_b128 v[110:113], v229 offset:0
	ds_read_b128 v[122:125], v229 offset:19968
	ds_read_b128 v[114:117], v229 offset:64
	ds_read_b128 v[126:129], v229 offset:20032
	ds_read_b128 v[118:121], v229 offset:128
	ds_read_b128 v[130:133], v229 offset:20096
	ds_read_b128 v[150:153], v230
	ds_read_b128 v[154:157], v230 offset:384
	ds_read_b128 v[158:161], v230 offset:768
	s_mov_b32 s62, -1
	s_mov_b32 s63, 0xffff
	s_mov_b64 exec, s[62:63]
	v_lshlrev_b32_e32 v64, 16, v66
	v_and_b32_e32 v65, 0xffff0000, v66
	v_pk_fma_f32 v[242:243], v[58:59], v[48:49], v[56:57]
	v_lshlrev_b32_e32 v58, 16, v67
	v_and_b32_e32 v59, 0xffff0000, v67
	v_pk_fma_f32 v[244:245], v[60:61], v[48:49], v[56:57]
	v_pk_fma_f32 v[242:243], v[60:61], v[50:51], v[242:243]
	v_pk_fma_f32 v[244:245], v[62:63], v[50:51], v[244:245]
	v_pk_fma_f32 v[242:243], v[62:63], v[52:53], v[242:243]
	v_pk_fma_f32 v[244:245], v[64:65], v[52:53], v[244:245]
	v_pk_fma_f32 v[242:243], v[64:65], v[54:55], v[242:243]
	v_pk_fma_f32 v[244:245], v[58:59], v[54:55], v[244:245]
	ds_write_b64 v226, v[242:243] offset:0
	v_cvt_pk_bf16_f32 v246, v242, v243
	ds_write_b64 v226, v[244:245] offset:400
	v_cvt_pk_bf16_f32 v247, v244, v245
	ds_write_b32 v227, v246 offset:0
	ds_write_b32 v227, v247 offset:208
	v_lshlrev_b32_e32 v60, 16, v68
	v_and_b32_e32 v61, 0xffff0000, v68
	v_pk_fma_f32 v[242:243], v[62:63], v[48:49], v[56:57]
	v_lshlrev_b32_e32 v62, 16, v69
	v_and_b32_e32 v63, 0xffff0000, v69
	v_pk_fma_f32 v[244:245], v[64:65], v[48:49], v[56:57]
	v_pk_fma_f32 v[242:243], v[64:65], v[50:51], v[242:243]
	v_pk_fma_f32 v[244:245], v[58:59], v[50:51], v[244:245]
	v_pk_fma_f32 v[242:243], v[58:59], v[52:53], v[242:243]
	v_pk_fma_f32 v[244:245], v[60:61], v[52:53], v[244:245]
	v_pk_fma_f32 v[242:243], v[60:61], v[54:55], v[242:243]
	v_pk_fma_f32 v[244:245], v[62:63], v[54:55], v[244:245]
	ds_write_b64 v226, v[242:243] offset:800
	v_cvt_pk_bf16_f32 v246, v242, v243
	ds_write_b64 v226, v[244:245] offset:1200
	v_cvt_pk_bf16_f32 v247, v244, v245
	ds_write_b32 v227, v246 offset:416
	ds_write_b32 v227, v247 offset:624
	v_lshlrev_b32_e32 v64, 16, v70
	v_and_b32_e32 v65, 0xffff0000, v70
	v_pk_fma_f32 v[242:243], v[58:59], v[48:49], v[56:57]
	v_lshlrev_b32_e32 v58, 16, v71
	v_and_b32_e32 v59, 0xffff0000, v71
	v_pk_fma_f32 v[244:245], v[60:61], v[48:49], v[56:57]
	v_pk_fma_f32 v[242:243], v[60:61], v[50:51], v[242:243]
	v_pk_fma_f32 v[244:245], v[62:63], v[50:51], v[244:245]
	v_pk_fma_f32 v[242:243], v[62:63], v[52:53], v[242:243]
	v_pk_fma_f32 v[244:245], v[64:65], v[52:53], v[244:245]
	v_pk_fma_f32 v[242:243], v[64:65], v[54:55], v[242:243]
	v_pk_fma_f32 v[244:245], v[58:59], v[54:55], v[244:245]
	ds_write_b64 v226, v[242:243] offset:1600
	v_cvt_pk_bf16_f32 v246, v242, v243
	ds_write_b64 v226, v[244:245] offset:2000
	v_cvt_pk_bf16_f32 v247, v244, v245
	ds_write_b32 v227, v246 offset:832
	ds_write_b32 v227, v247 offset:1040
	v_lshlrev_b32_e32 v60, 16, v72
	v_and_b32_e32 v61, 0xffff0000, v72
	v_pk_fma_f32 v[242:243], v[62:63], v[48:49], v[56:57]
	v_lshlrev_b32_e32 v62, 16, v73
	v_and_b32_e32 v63, 0xffff0000, v73
	v_pk_fma_f32 v[244:245], v[64:65], v[48:49], v[56:57]
	v_pk_fma_f32 v[242:243], v[64:65], v[50:51], v[242:243]
	v_pk_fma_f32 v[244:245], v[58:59], v[50:51], v[244:245]
	v_pk_fma_f32 v[242:243], v[58:59], v[52:53], v[242:243]
	v_pk_fma_f32 v[244:245], v[60:61], v[52:53], v[244:245]
	v_pk_fma_f32 v[242:243], v[60:61], v[54:55], v[242:243]
	v_pk_fma_f32 v[244:245], v[62:63], v[54:55], v[244:245]
	ds_write_b64 v226, v[242:243] offset:2400
	v_cvt_pk_bf16_f32 v246, v242, v243
	ds_write_b64 v226, v[244:245] offset:2800
	v_cvt_pk_bf16_f32 v247, v244, v245
	ds_write_b32 v227, v246 offset:1248
	ds_write_b32 v227, v247 offset:1456
	v_lshlrev_b32_e32 v64, 16, v74
	v_and_b32_e32 v65, 0xffff0000, v74
	v_pk_fma_f32 v[242:243], v[58:59], v[48:49], v[56:57]
	v_lshlrev_b32_e32 v58, 16, v75
	v_and_b32_e32 v59, 0xffff0000, v75
	v_pk_fma_f32 v[244:245], v[60:61], v[48:49], v[56:57]
	v_pk_fma_f32 v[242:243], v[60:61], v[50:51], v[242:243]
	v_pk_fma_f32 v[244:245], v[62:63], v[50:51], v[244:245]
	v_pk_fma_f32 v[242:243], v[62:63], v[52:53], v[242:243]
	v_pk_fma_f32 v[244:245], v[64:65], v[52:53], v[244:245]
	v_pk_fma_f32 v[242:243], v[64:65], v[54:55], v[242:243]
	v_pk_fma_f32 v[244:245], v[58:59], v[54:55], v[244:245]
	ds_write_b64 v226, v[242:243] offset:3200
	v_cvt_pk_bf16_f32 v246, v242, v243
	ds_write_b64 v226, v[244:245] offset:3600
	v_cvt_pk_bf16_f32 v247, v244, v245
	ds_write_b32 v227, v246 offset:1664
	ds_write_b32 v227, v247 offset:1872
	v_lshlrev_b32_e32 v60, 16, v76
	v_and_b32_e32 v61, 0xffff0000, v76
	v_pk_fma_f32 v[242:243], v[62:63], v[48:49], v[56:57]
	v_lshlrev_b32_e32 v62, 16, v77
	v_and_b32_e32 v63, 0xffff0000, v77
	v_pk_fma_f32 v[244:245], v[64:65], v[48:49], v[56:57]
	v_pk_fma_f32 v[242:243], v[64:65], v[50:51], v[242:243]
	v_pk_fma_f32 v[244:245], v[58:59], v[50:51], v[244:245]
	v_pk_fma_f32 v[242:243], v[58:59], v[52:53], v[242:243]
	v_pk_fma_f32 v[244:245], v[60:61], v[52:53], v[244:245]
	v_pk_fma_f32 v[242:243], v[60:61], v[54:55], v[242:243]
	v_pk_fma_f32 v[244:245], v[62:63], v[54:55], v[244:245]
	ds_write_b64 v226, v[242:243] offset:4000
	v_cvt_pk_bf16_f32 v246, v242, v243
	ds_write_b64 v226, v[244:245] offset:4400
	v_cvt_pk_bf16_f32 v247, v244, v245
	ds_write_b32 v227, v246 offset:2080
	ds_write_b32 v227, v247 offset:2288
	v_lshlrev_b32_e32 v64, 16, v78
	v_and_b32_e32 v65, 0xffff0000, v78
	v_pk_fma_f32 v[242:243], v[58:59], v[48:49], v[56:57]
	v_lshlrev_b32_e32 v58, 16, v79
	v_and_b32_e32 v59, 0xffff0000, v79
	v_pk_fma_f32 v[244:245], v[60:61], v[48:49], v[56:57]
	v_pk_fma_f32 v[242:243], v[60:61], v[50:51], v[242:243]
	v_pk_fma_f32 v[244:245], v[62:63], v[50:51], v[244:245]
	v_pk_fma_f32 v[242:243], v[62:63], v[52:53], v[242:243]
	v_pk_fma_f32 v[244:245], v[64:65], v[52:53], v[244:245]
	v_pk_fma_f32 v[242:243], v[64:65], v[54:55], v[242:243]
	v_pk_fma_f32 v[244:245], v[58:59], v[54:55], v[244:245]
	ds_write_b64 v226, v[242:243] offset:4800
	v_cvt_pk_bf16_f32 v246, v242, v243
	ds_write_b64 v226, v[244:245] offset:5200
	v_cvt_pk_bf16_f32 v247, v244, v245
	ds_write_b32 v227, v246 offset:2496
	ds_write_b32 v227, v247 offset:2704
	v_lshlrev_b32_e32 v60, 16, v80
	v_and_b32_e32 v61, 0xffff0000, v80
	v_pk_fma_f32 v[242:243], v[62:63], v[48:49], v[56:57]
	v_lshlrev_b32_e32 v62, 16, v81
	v_and_b32_e32 v63, 0xffff0000, v81
	v_pk_fma_f32 v[244:245], v[64:65], v[48:49], v[56:57]
	v_pk_fma_f32 v[242:243], v[64:65], v[50:51], v[242:243]
	v_pk_fma_f32 v[244:245], v[58:59], v[50:51], v[244:245]
	v_pk_fma_f32 v[242:243], v[58:59], v[52:53], v[242:243]
	v_pk_fma_f32 v[244:245], v[60:61], v[52:53], v[244:245]
	v_pk_fma_f32 v[242:243], v[60:61], v[54:55], v[242:243]
	v_pk_fma_f32 v[244:245], v[62:63], v[54:55], v[244:245]
	ds_write_b64 v226, v[242:243] offset:5600
	v_cvt_pk_bf16_f32 v246, v242, v243
	ds_write_b64 v226, v[244:245] offset:6000
	v_cvt_pk_bf16_f32 v247, v244, v245
	ds_write_b32 v227, v246 offset:2912
	ds_write_b32 v227, v247 offset:3120
	s_mov_b64 exec, -1
	s_waitcnt lgkmcnt(0)
	ds_read_b128 v[98:101], v228 offset:0
	ds_read_b128 v[102:105], v228 offset:64
	ds_read_b128 v[106:109], v228 offset:128
	ds_read_b128 v[162:165], v231
	s_waitcnt lgkmcnt(0)
	v_mfma_f32_16x16x32_bf16 v[134:137], v[110:113], v[98:101], 0
	v_mfma_f32_16x16x32_bf16 v[138:141], v[122:125], v[98:101], 0
	v_mfma_f32_16x16x32_bf16 v[134:137], v[114:117], v[102:105], v[134:137]
	v_mfma_f32_16x16x32_bf16 v[138:141], v[126:129], v[102:105], v[138:141]
	v_mfma_f32_16x16x32_bf16 v[134:137], v[118:121], v[106:109], v[134:137]
	v_mfma_f32_16x16x32_bf16 v[138:141], v[130:133], v[106:109], v[138:141]
	ds_read_b128 v[110:113], v229 offset:3328
	ds_read_b128 v[122:125], v229 offset:23296
	ds_read_b128 v[114:117], v229 offset:3392
	ds_read_b128 v[126:129], v229 offset:23360
	ds_read_b128 v[118:121], v229 offset:3456
	ds_read_b128 v[130:133], v229 offset:23424
	s_nop 7
	s_nop 7
	v_pk_fma_f32 v[166:167], v[134:135], s[66:67], v[150:151] op_sel_hi:[1,0,1]
	v_pk_fma_f32 v[168:169], v[136:137], s[66:67], v[152:153] op_sel_hi:[1,0,1]
	v_pk_fma_f32 v[204:205], v[138:139], s[66:67], v[154:155] op_sel_hi:[1,0,1]
	v_pk_fma_f32 v[206:207], v[140:141], s[66:67], v[156:157] op_sel_hi:[1,0,1]
	v_exp_f32_e32 v166, v166
	v_exp_f32_e32 v167, v167
	v_exp_f32_e32 v168, v168
	v_exp_f32_e32 v169, v169
	v_exp_f32_e32 v204, v204
	v_exp_f32_e32 v205, v205
	v_exp_f32_e32 v206, v206
	v_exp_f32_e32 v207, v207
	v_pk_add_f32 v[166:167], v[166:167], 1.0 op_sel_hi:[1,0]
	v_pk_add_f32 v[168:169], v[168:169], 1.0 op_sel_hi:[1,0]
	v_pk_add_f32 v[204:205], v[204:205], 1.0 op_sel_hi:[1,0]
	v_pk_add_f32 v[206:207], v[206:207], 1.0 op_sel_hi:[1,0]
	v_rcp_f32_e32 v166, v166
	v_rcp_f32_e32 v167, v167
	v_rcp_f32_e32 v168, v168
	v_rcp_f32_e32 v169, v169
	v_rcp_f32_e32 v204, v204
	v_rcp_f32_e32 v205, v205
	v_rcp_f32_e32 v206, v206
	v_rcp_f32_e32 v207, v207
	v_pk_mul_f32 v[208:209], v[158:159], v[166:167]
	v_pk_mul_f32 v[210:211], v[160:161], v[168:169]
	v_pk_mul_f32 v[204:205], v[162:163], v[204:205]
	v_pk_mul_f32 v[206:207], v[164:165], v[206:207]
	ds_read_b128 v[150:153], v230 offset:64
	ds_read_b128 v[154:157], v230 offset:448
	ds_read_b128 v[158:161], v230 offset:832
	ds_read_b128 v[162:165], v231 offset:64
	v_exp_f32_e32 v166, v208
	v_exp_f32_e32 v167, v209
	v_exp_f32_e32 v168, v210
	v_exp_f32_e32 v169, v211
	v_pk_fma_f32 v[216:217], v[208:209], s[66:67], v[248:249] op_sel:[0,1,0] op_sel_hi:[1,1,0]
	v_pk_fma_f32 v[218:219], v[210:211], s[66:67], v[248:249] op_sel:[0,1,0] op_sel_hi:[1,1,0]
	v_pk_fma_f32 v[216:217], v[208:209], v[216:217], v[248:249] op_sel:[0,0,1] op_sel_hi:[1,1,1]
	v_pk_fma_f32 v[218:219], v[210:211], v[218:219], v[248:249] op_sel:[0,0,1] op_sel_hi:[1,1,1]
	v_min3_f32 v212, v208, v209, v210
	v_pk_fma_f32 v[216:217], v[208:209], v[216:217], v[250:251] op_sel_hi:[1,1,0]
	v_pk_fma_f32 v[218:219], v[210:211], v[218:219], v[250:251] op_sel_hi:[1,1,0]
	v_min_f32_e32 v212, v212, v211
	v_pk_fma_f32 v[216:217], v[208:209], v[216:217], v[250:251] op_sel:[0,0,1] op_sel_hi:[1,1,1]
	v_pk_fma_f32 v[218:219], v[210:211], v[218:219], v[250:251] op_sel:[0,0,1] op_sel_hi:[1,1,1]
	v_cmp_nlt_f32_e32 vcc, 0xbe38aa3b, v212
	v_pk_mul_f32 v[216:217], v[216:217], v[208:209]
	v_pk_mul_f32 v[218:219], v[218:219], v[210:211]
	s_cbranch_vccnz .Lscan1_far0

.LBB0_424:
	s_andn2_b64 vcc, exec, s[6:7]
	s_cbranch_vccnz .LBB0_574
	v_readlane_b32 s6, v254, 0
	v_readlane_b32 s7, v254, 1
	s_load_dwordx4 s[12:15], s[6:7], 0xb8
	v_mov_b32_e32 v98, v192
	s_mov_b32 s66, s20
	s_and_b64 vcc, exec, s[4:5]
	v_readfirstlane_b32 s0, v98
	s_cbranch_vccnz .LBB0_548
	s_waitcnt lgkmcnt(0)
	s_mov_b64 s[16:17], s[12:13]
	s_mov_b64 s[18:19], s[14:15]
	s_mov_b32 s20, s66
	s_load_dwordx4 s[8:11], s[6:7], 0x18
	s_load_dwordx2 s[12:13], s[6:7], 0x30
	s_load_dwordx4 s[24:27], s[6:7], 0x40
	v_readfirstlane_b32 s21, v192
	s_lshr_b32 s21, s21, 6
	s_add_u32 s28, s18, 0x8f29000
	s_addc_u32 s29, s19, 0
	s_add_u32 s30, s16, 0x3db4000
	s_addc_u32 s31, s17, 0
	s_add_u32 s34, s18, 0xf0b5000
	s_addc_u32 s35, s19, 0
	v_and_b32_e32 v238, 63, v192
	v_and_b32_e32 v239, 15, v192
	v_bfe_u32 v240, v192, 4, 2
	s_mul_i32 s0, s21, 0x2600
	s_add_i32 s0, s0, 0xa080
	v_lshl_add_u32 v226, v238, 3, s0
	v_lshl_add_u32 v227, v238, 2, s0
	v_add_u32_e32 v227, 0x1900, v227
	v_mul_u32_u24_e32 v229, 0xd0, v239
	v_lshl_add_u32 v229, v240, 4, v229
	v_add_u32_e32 v228, s0, v229
	v_add_u32_e32 v228, 0x1900, v228
	v_lshlrev_b32_e32 v237, 4, v240
	v_add_u32_e32 v230, 0x9c00, v237
	v_mul_u32_u24_e32 v231, 0x190, v239
	v_add3_u32 v231, v231, v237, s0
	v_and_or_b32 v232, v238, 48, 15
	v_lshlrev_b32_e32 v232, 2, v232
	v_min_u32_e32 v241, 47, v238
	v_lshlrev_b32_e32 v233, 2, v241
	v_lshlrev_b32_e32 v234, 3, v241
	v_mul_u32_u24_e32 v235, 0x1800, v239
	v_lshl_add_u32 v235, v240, 3, v235
	v_mul_u32_u24_e32 v236, 0xc00, v239
	v_lshl_add_u32 v236, v240, 3, v236
	s_waitcnt lgkmcnt(0)
	s_mul_i32 s0, s20, 0x6000
	s_add_u32 s8, s8, s0
	s_addc_u32 s9, s9, 0
	s_mul_i32 s0, s20, 0x1800
	s_add_u32 s10, s10, s0
	s_addc_u32 s11, s11, 0
	s_add_u32 s12, s12, s0
	s_addc_u32 s13, s13, 0
	s_add_u32 s24, s24, s0
	s_addc_u32 s25, s25, 0
	s_add_u32 s26, s26, s0
	s_addc_u32 s27, s27, 0
	s_mov_b32 s38, -1
	s_mov_b32 s23, s2
	s_cmpk_lt_u32 s23, 0x2b0
	s_cbranch_scc0 .Lscan2_unit_test
	s_lshr_b32 s0, s23, 4
	s_lshl_b32 s0, s0, 3
	s_add_i32 s0, s0, s21
	s_mul_i32 s39, s0, 0x5f5
	s_lshr_b32 s39, s39, 16
	s_mul_i32 s62, s39, 43
	s_sub_i32 s0, s0, s62
	s_mul_i32 s39, s39, 0x810
	s_mul_i32 s0, s0, 48
	s_add_i32 s39, s39, s0
	s_mul_i32 s44, s39, 0x1800
	s_mul_hi_u32 s45, s39, 0x1800
	s_and_b32 s0, s23, 15
	s_mul_i32 s0, s0, 0xc0
	s_add_i32 s0, s0, 0xc00
	s_add_u32 s44, s44, s0
	s_addc_u32 s45, s45, 0
	s_add_u32 s44, s44, s28
	s_addc_u32 s45, s45, s29
	s_add_u32 s62, s44, 0xffffb800
	s_addc_u32 s63, s45, -1
	global_load_dword v222, v233, s[62:63]
	s_add_u32 s62, s62, 0x1800
	s_addc_u32 s63, s63, 0
	global_load_dword v223, v233, s[62:63]
	s_add_u32 s62, s62, 0x1800
	s_addc_u32 s63, s63, 0
	global_load_dword v224, v233, s[62:63]
	s_mov_b64 s[62:63], s[44:45]
	global_load_dword v66, v233, s[62:63]
	s_add_u32 s62, s62, 0x1800
	s_addc_u32 s63, s63, 0
	global_load_dword v67, v233, s[62:63]
	s_add_u32 s62, s62, 0x1800
	s_addc_u32 s63, s63, 0
	global_load_dword v68, v233, s[62:63]
	s_add_u32 s62, s62, 0x1800
	s_addc_u32 s63, s63, 0
	global_load_dword v69, v233, s[62:63]
	s_add_u32 s62, s62, 0x1800
	s_addc_u32 s63, s63, 0
	global_load_dword v70, v233, s[62:63]
	s_add_u32 s62, s62, 0x1800
	s_addc_u32 s63, s63, 0
	global_load_dword v71, v233, s[62:63]
	s_add_u32 s62, s62, 0x1800
	s_addc_u32 s63, s63, 0
	global_load_dword v72, v233, s[62:63]
	s_add_u32 s62, s62, 0x1800
	s_addc_u32 s63, s63, 0
	global_load_dword v73, v233, s[62:63]
	s_add_u32 s62, s62, 0x1800
	s_addc_u32 s63, s63, 0
	global_load_dword v74, v233, s[62:63]
	s_add_u32 s62, s62, 0x1800
	s_addc_u32 s63, s63, 0
	global_load_dword v75, v233, s[62:63]
	s_add_u32 s62, s62, 0x1800
	s_addc_u32 s63, s63, 0
	global_load_dword v76, v233, s[62:63]
	s_add_u32 s62, s62, 0x1800
	s_addc_u32 s63, s63, 0
	global_load_dword v77, v233, s[62:63]
	s_add_u32 s62, s62, 0x1800
	s_addc_u32 s63, s63, 0
	global_load_dword v78, v233, s[62:63]
	s_add_u32 s62, s62, 0x1800
	s_addc_u32 s63, s63, 0
	global_load_dword v79, v233, s[62:63]
	s_add_u32 s62, s62, 0x1800
	s_addc_u32 s63, s63, 0
	global_load_dword v80, v233, s[62:63]
	s_add_u32 s62, s62, 0x1800
	s_addc_u32 s63, s63, 0
	global_load_dword v81, v233, s[62:63]
	s_add_u32 s62, s62, 0x1800
	s_addc_u32 s63, s63, 0
	s_mov_b64 s[44:45], s[62:63]
	s_branch .Lscan2_unit_test
.Lscan2_unit:
	s_and_b32 s37, s23, 15
	s_lshr_b32 s0, s23, 4
	s_lshl_b32 s0, s0, 3
	s_add_i32 s0, s0, s21
	s_mul_i32 s55, s0, 0x5f5
	s_lshr_b32 s55, s55, 16
	s_mul_i32 s56, s55, 43
	s_sub_i32 s56, s0, s56
	s_mul_i32 s57, s55, 0x810
	s_mul_i32 s39, s56, 48
	s_add_i32 s57, s57, s39
	s_add_i32 s0, s23, s42
	s_cmpk_lt_u32 s0, 0x2b0
	s_cselect_b32 s0, s0, s23
	s_lshr_b32 s39, s0, 4
	s_lshl_b32 s39, s39, 3
	s_add_i32 s39, s39, s21
	s_mul_i32 s62, s39, 0x5f5
	s_lshr_b32 s62, s62, 16
	s_mul_i32 s63, s62, 43
	s_sub_i32 s39, s39, s63
	s_mul_i32 s62, s62, 0x810
	s_mul_i32 s39, s39, 48
	s_add_i32 s62, s62, s39
	s_mul_i32 s61, s62, 0x1800
	s_mul_hi_u32 s65, s62, 0x1800
	s_and_b32 s39, s0, 15
	s_mul_i32 s39, s39, 0xc0
	s_add_i32 s39, s39, 0xc00
	s_add_u32 s61, s61, s39
	s_addc_u32 s65, s65, 0
	s_add_u32 s61, s61, s28
	s_addc_u32 s65, s65, s29
	s_mul_i32 s39, s55, 43
	s_add_i32 s39, s39, s56
	s_mul_i32 s39, s39, 0x1800
	s_mul_i32 s0, s37, 0x180
	s_add_i32 s39, s39, s0
	s_add_u32 s62, s30, s39
	s_addc_u32 s63, s31, 0
	global_load_dwordx4 v[0:3], v237, s[62:63] offset:0
	global_load_dwordx4 v[4:7], v237, s[62:63] offset:64
	global_load_dwordx4 v[8:11], v237, s[62:63] offset:128
	global_load_dwordx4 v[12:15], v237, s[62:63] offset:192
	global_load_dwordx4 v[16:19], v237, s[62:63] offset:256
	global_load_dwordx4 v[20:23], v237, s[62:63] offset:320
	s_mul_i32 s6, s57, 0x1800
	s_mul_hi_u32 s7, s57, 0x1800
	s_mul_i32 s39, s37, 0xc0
	s_add_u32 s6, s6, s39
	s_addc_u32 s7, s7, 0
	s_add_u32 s6, s6, s28
	s_addc_u32 s7, s7, s29
	s_mul_i32 s100, s57, 0xc00
	s_mul_hi_u32 s101, s57, 0xc00
	s_add_u32 s100, s100, s39
	s_addc_u32 s101, s101, 0
	s_add_u32 s100, s100, s34
	s_addc_u32 s101, s101, s35
	s_cmp_eq_u32 s37, s38
	s_cbranch_scc1 .Lscan2_staged
	s_mul_i32 s39, s37, 0x180
	s_add_u32 s62, s8, s39
	s_addc_u32 s63, s9, 0
	global_load_dwordx2 v[48:49], v234, s[62:63]
	s_add_u32 s62, s62, 0x1800
	s_addc_u32 s63, s63, 0
	global_load_dwordx2 v[50:51], v234, s[62:63]
	s_add_u32 s62, s62, 0x1800
	s_addc_u32 s63, s63, 0
	global_load_dwordx2 v[52:53], v234, s[62:63]
	s_add_u32 s62, s62, 0x1800
	s_addc_u32 s63, s63, 0
	global_load_dwordx2 v[54:55], v234, s[62:63]
	s_add_u32 s62, s10, s39
	s_addc_u32 s63, s11, 0
	global_load_dwordx2 v[56:57], v234, s[62:63]
	s_lshl_b32 s0, s20, 4
	s_add_i32 s0, s0, s37
	s_mul_i32 s0, s0, 0x4800
	s_add_u32 s62, s16, 0x3688000
	s_addc_u32 s63, s17, 0
	s_add_u32 s62, s62, s0
	s_addc_u32 s63, s63, 0
	v_add_u32_e32 v239, 0, v192
	v_mul_u32_u24_e32 v240, 0xaaab, v239
	v_lshrrev_b32_e32 v240, 19, v240
	v_mul_u32_u24_e32 v241, 12, v240
	v_sub_u32_e32 v241, v239, v241
	v_lshlrev_b32_e32 v241, 4, v241
	v_mul_u32_u24_e32 v118, 0xd0, v240
	v_add_u32_e32 v118, v118, v241
	v_mul_u32_u24_e32 v243, 0xc0, v240
	v_add_u32_e32 v243, v243, v241
	v_cmp_lt_u32_e32 vcc, 95, v240
	s_nop 1
	v_mov_b32_e32 v244, 0x8b800
	v_cndmask_b32_e32 v244, 0, v244, vcc
	v_add_u32_e32 v243, v243, v244
	global_load_dwordx4 v[98:101], v243, s[62:63]
	v_add_u32_e32 v239, 512, v192
	v_mul_u32_u24_e32 v240, 0xaaab, v239
	v_lshrrev_b32_e32 v240, 19, v240
	v_mul_u32_u24_e32 v241, 12, v240
	v_sub_u32_e32 v241, v239, v241
	v_lshlrev_b32_e32 v241, 4, v241
	v_mul_u32_u24_e32 v119, 0xd0, v240
	v_add_u32_e32 v119, v119, v241
	v_mul_u32_u24_e32 v243, 0xc0, v240
	v_add_u32_e32 v243, v243, v241
	v_cmp_lt_u32_e32 vcc, 95, v240
	s_nop 1
	v_mov_b32_e32 v244, 0x8b800
	v_cndmask_b32_e32 v244, 0, v244, vcc
	v_add_u32_e32 v243, v243, v244
	global_load_dwordx4 v[102:105], v243, s[62:63]
	v_add_u32_e32 v239, 1024, v192
	v_mul_u32_u24_e32 v240, 0xaaab, v239
	v_lshrrev_b32_e32 v240, 19, v240
	v_mul_u32_u24_e32 v241, 12, v240
	v_sub_u32_e32 v241, v239, v241
	v_lshlrev_b32_e32 v241, 4, v241
	v_mul_u32_u24_e32 v120, 0xd0, v240
	v_add_u32_e32 v120, v120, v241
	v_mul_u32_u24_e32 v243, 0xc0, v240
	v_add_u32_e32 v243, v243, v241
	v_cmp_lt_u32_e32 vcc, 95, v240
	s_nop 1
	v_mov_b32_e32 v244, 0x8b800
	v_cndmask_b32_e32 v244, 0, v244, vcc
	v_add_u32_e32 v243, v243, v244
	global_load_dwordx4 v[106:109], v243, s[62:63]
	v_add_u32_e32 v239, 1536, v192
	v_mul_u32_u24_e32 v240, 0xaaab, v239
	v_lshrrev_b32_e32 v240, 19, v240
	v_mul_u32_u24_e32 v241, 12, v240
	v_sub_u32_e32 v241, v239, v241
	v_lshlrev_b32_e32 v241, 4, v241
	v_mul_u32_u24_e32 v121, 0xd0, v240
	v_add_u32_e32 v121, v121, v241
	v_mul_u32_u24_e32 v243, 0xc0, v240
	v_add_u32_e32 v243, v243, v241
	v_cmp_lt_u32_e32 vcc, 95, v240
	s_nop 1
	v_mov_b32_e32 v244, 0x8b800
	v_cndmask_b32_e32 v244, 0, v244, vcc
	v_add_u32_e32 v243, v243, v244
	global_load_dwordx4 v[110:113], v243, s[62:63]
	v_add_u32_e32 v239, 2048, v192
	v_mul_u32_u24_e32 v240, 0xaaab, v239
	v_lshrrev_b32_e32 v240, 19, v240
	v_mul_u32_u24_e32 v241, 12, v240
	v_sub_u32_e32 v241, v239, v241
	v_lshlrev_b32_e32 v241, 4, v241
	v_mul_u32_u24_e32 v122, 0xd0, v240
	v_add_u32_e32 v122, v122, v241
	v_mul_u32_u24_e32 v243, 0xc0, v240
	v_add_u32_e32 v243, v243, v241
	v_cmp_lt_u32_e32 vcc, 95, v240
	s_nop 1
	v_mov_b32_e32 v244, 0x8b800
	v_cndmask_b32_e32 v244, 0, v244, vcc
	v_add_u32_e32 v243, v243, v244
	v_cmp_gt_u32_e32 vcc, 0x900, v239
	s_and_b64 exec, exec, vcc
	global_load_dwordx4 v[114:117], v243, s[62:63]
	s_mov_b64 exec, -1
	v_cmp_gt_u32_e32 vcc, 0x60, v192
	s_and_b64 exec, exec, vcc
	s_mul_i32 s0, s37, 0x180
	v_lshl_add_u32 v239, v192, 2, s0
	global_load_dword v123, v239, s[12:13]
	global_load_dword v124, v239, s[24:25]
	global_load_dword v125, v239, s[26:27]
	s_mov_b64 exec, -1
	s_waitcnt lgkmcnt(0)
	s_barrier
	s_waitcnt vmcnt(0)
	ds_write_b128 v118, v[98:101]
	ds_write_b128 v119, v[102:105]
	ds_write_b128 v120, v[106:109]
	ds_write_b128 v121, v[110:113]
	v_cmp_gt_u32_e32 vcc, 0x100, v192
	s_and_b64 exec, exec, vcc
	ds_write_b128 v122, v[114:117]
	s_mov_b64 exec, -1
	v_cmp_gt_u32_e32 vcc, 0x60, v192
	s_and_b64 exec, exec, vcc
	v_lshlrev_b32_e32 v240, 2, v192
	v_mul_f32_e32 v123, 0xbfb8aa3b, v123
	v_mul_f32_e32 v124, 0xbfb8aa3b, v124
	ds_write_b32 v240, v123 offset:39936
	ds_write_b32 v240, v124 offset:40320
	v_mul_f32_e32 v244, 0xbfb8aa3b, v125
	v_exp_f32_e32 v244, v244
	s_nop 0
	v_add_f32_e32 v245, 1.0, v244
	v_log_f32_e32 v245, v245
	v_fmamk_f32 v246, v244, 0xbe800000, v194
	v_fma_f32 v246, -v244, v246, 0.5
	v_fma_f32 v246, -v244, v246, 1.0
	v_mul_f32_e32 v246, v244, v246
	v_mul_f32_e32 v247, 0x3f317217, v245
	v_fma_f32 v247, v245, s76, -v247
	v_fmac_f32_e32 v247, 0x3377d1cf, v245
	v_fmac_f32_e32 v247, 0x3f317217, v245
	v_cmp_ngt_f32_e32 vcc, s90, v244
	s_nop 1
	v_cndmask_b32_e32 v246, v246, v247, vcc
	v_mul_f32_e32 v246, 0xc138aa3b, v246
	ds_write_b32 v240, v246 offset:40704
	s_mov_b64 exec, -1
	s_mov_b32 s38, s37
	s_waitcnt lgkmcnt(0)
	s_barrier
.Lscan2_staged:
	s_mov_b32 s4, 0xbfb8aa3b
	s_mov_b32 s5, 0xbd2ec3ff
	v_mov_b32_e32 v248, 0xbe1d955b
	v_mov_b32_e32 v249, 0xbee35847
	v_mov_b32_e32 v250, 0xbf75fdf0
	v_mov_b32_e32 v251, 0xbfb17218
	v_mov_b32_e32 v36, 0xbdd2d3e8
	v_mov_b32_e32 v37, 0xc0135761
	s_cmp_eq_u32 s56, 0
	s_cbranch_scc1 .Lscan2_hzero
	v_lshlrev_b32_e32 v58, 16, v222
	v_and_b32_e32 v59, 0xffff0000, v222
	v_lshlrev_b32_e32 v60, 16, v223
	v_and_b32_e32 v61, 0xffff0000, v223
	v_lshlrev_b32_e32 v62, 16, v224
	v_and_b32_e32 v63, 0xffff0000, v224
	s_branch .Lscan2_hdone

.Lscan2_sub:
	global_load_dwordx2 v[24:25], v235, s[6:7] offset:0
	global_load_dwordx2 v[26:27], v235, s[6:7] offset:32
	global_load_dwordx2 v[28:29], v235, s[6:7] offset:64
	global_load_dwordx2 v[30:31], v235, s[6:7] offset:96
	global_load_dwordx2 v[32:33], v235, s[6:7] offset:128
	global_load_dwordx2 v[34:35], v235, s[6:7] offset:160
	s_cmp_eq_u32 s64, 2
	s_cselect_b32 s44, s61, s44
	s_cselect_b32 s45, s65, s45
	s_add_u32 s62, s44, 0xffffb800
	s_addc_u32 s63, s45, -1
	global_load_dword v222, v233, s[62:63]
	s_add_u32 s62, s62, 0x1800
	s_addc_u32 s63, s63, 0
	global_load_dword v223, v233, s[62:63]
	s_add_u32 s62, s62, 0x1800
	s_addc_u32 s63, s63, 0
	global_load_dword v224, v233, s[62:63]
	s_mov_b64 s[62:63], s[44:45]
	global_load_dword v82, v233, s[62:63]
	s_add_u32 s62, s62, 0x1800
	s_addc_u32 s63, s63, 0
	global_load_dword v83, v233, s[62:63]
	s_add_u32 s62, s62, 0x1800
	s_addc_u32 s63, s63, 0
	global_load_dword v84, v233, s[62:63]
	s_add_u32 s62, s62, 0x1800
	s_addc_u32 s63, s63, 0
	global_load_dword v85, v233, s[62:63]
	s_add_u32 s62, s62, 0x1800
	s_addc_u32 s63, s63, 0
	global_load_dword v86, v233, s[62:63]
	s_add_u32 s62, s62, 0x1800
	s_addc_u32 s63, s63, 0
	global_load_dword v87, v233, s[62:63]
	s_add_u32 s62, s62, 0x1800
	s_addc_u32 s63, s63, 0
	global_load_dword v88, v233, s[62:63]
	s_add_u32 s62, s62, 0x1800
	s_addc_u32 s63, s63, 0
	global_load_dword v89, v233, s[62:63]
	s_add_u32 s62, s62, 0x1800
	s_addc_u32 s63, s63, 0
	global_load_dword v90, v233, s[62:63]
	s_add_u32 s62, s62, 0x1800
	s_addc_u32 s63, s63, 0
	global_load_dword v91, v233, s[62:63]
	s_add_u32 s62, s62, 0x1800
	s_addc_u32 s63, s63, 0
	global_load_dword v92, v233, s[62:63]
	s_add_u32 s62, s62, 0x1800
	s_addc_u32 s63, s63, 0
	global_load_dword v93, v233, s[62:63]
	s_add_u32 s62, s62, 0x1800
	s_addc_u32 s63, s63, 0
	global_load_dword v94, v233, s[62:63]
	s_add_u32 s62, s62, 0x1800
	s_addc_u32 s63, s63, 0
	global_load_dword v95, v233, s[62:63]
	s_add_u32 s62, s62, 0x1800
	s_addc_u32 s63, s63, 0
	global_load_dword v96, v233, s[62:63]
	s_add_u32 s62, s62, 0x1800
	s_addc_u32 s63, s63, 0
	global_load_dword v97, v233, s[62:63]
	s_add_u32 s62, s62, 0x1800
	s_addc_u32 s63, s63, 0
	s_mov_b64 s[44:45], s[62:63]
	ds_read_b128 v[110:113], v229 offset:0
	ds_read_b128 v[122:125], v229 offset:19968
	ds_read_b128 v[114:117], v229 offset:64
	ds_read_b128 v[126:129], v229 offset:20032
	ds_read_b128 v[118:121], v229 offset:128
	ds_read_b128 v[130:133], v229 offset:20096
	ds_read_b128 v[150:153], v230
	ds_read_b128 v[154:157], v230 offset:384
	ds_read_b128 v[158:161], v230 offset:768
	s_mov_b32 s62, -1
	s_mov_b32 s63, 0xffff
	s_mov_b64 exec, s[62:63]
	v_lshlrev_b32_e32 v64, 16, v66
	v_and_b32_e32 v65, 0xffff0000, v66
	v_pk_fma_f32 v[242:243], v[58:59], v[48:49], v[56:57]
	v_lshlrev_b32_e32 v58, 16, v67
	v_and_b32_e32 v59, 0xffff0000, v67
	v_pk_fma_f32 v[244:245], v[60:61], v[48:49], v[56:57]
	v_pk_fma_f32 v[242:243], v[60:61], v[50:51], v[242:243]
	v_pk_fma_f32 v[244:245], v[62:63], v[50:51], v[244:245]
	v_pk_fma_f32 v[242:243], v[62:63], v[52:53], v[242:243]
	v_pk_fma_f32 v[244:245], v[64:65], v[52:53], v[244:245]
	v_pk_fma_f32 v[242:243], v[64:65], v[54:55], v[242:243]
	v_pk_fma_f32 v[244:245], v[58:59], v[54:55], v[244:245]
	ds_write_b64 v226, v[242:243] offset:0
	v_cvt_pk_bf16_f32 v246, v242, v243
	ds_write_b64 v226, v[244:245] offset:400
	v_cvt_pk_bf16_f32 v247, v244, v245
	ds_write_b32 v227, v246 offset:0
	ds_write_b32 v227, v247 offset:208
	v_lshlrev_b32_e32 v60, 16, v68
	v_and_b32_e32 v61, 0xffff0000, v68
	v_pk_fma_f32 v[242:243], v[62:63], v[48:49], v[56:57]
	v_lshlrev_b32_e32 v62, 16, v69
	v_and_b32_e32 v63, 0xffff0000, v69
	v_pk_fma_f32 v[244:245], v[64:65], v[48:49], v[56:57]
	v_pk_fma_f32 v[242:243], v[64:65], v[50:51], v[242:243]
	v_pk_fma_f32 v[244:245], v[58:59], v[50:51], v[244:245]
	v_pk_fma_f32 v[242:243], v[58:59], v[52:53], v[242:243]
	v_pk_fma_f32 v[244:245], v[60:61], v[52:53], v[244:245]
	v_pk_fma_f32 v[242:243], v[60:61], v[54:55], v[242:243]
	v_pk_fma_f32 v[244:245], v[62:63], v[54:55], v[244:245]
	ds_write_b64 v226, v[242:243] offset:800
	v_cvt_pk_bf16_f32 v246, v242, v243
	ds_write_b64 v226, v[244:245] offset:1200
	v_cvt_pk_bf16_f32 v247, v244, v245
	ds_write_b32 v227, v246 offset:416
	ds_write_b32 v227, v247 offset:624
	v_lshlrev_b32_e32 v64, 16, v70
	v_and_b32_e32 v65, 0xffff0000, v70
	v_pk_fma_f32 v[242:243], v[58:59], v[48:49], v[56:57]
	v_lshlrev_b32_e32 v58, 16, v71
	v_and_b32_e32 v59, 0xffff0000, v71
	v_pk_fma_f32 v[244:245], v[60:61], v[48:49], v[56:57]
	v_pk_fma_f32 v[242:243], v[60:61], v[50:51], v[242:243]
	v_pk_fma_f32 v[244:245], v[62:63], v[50:51], v[244:245]
	v_pk_fma_f32 v[242:243], v[62:63], v[52:53], v[242:243]
	v_pk_fma_f32 v[244:245], v[64:65], v[52:53], v[244:245]
	v_pk_fma_f32 v[242:243], v[64:65], v[54:55], v[242:243]
	v_pk_fma_f32 v[244:245], v[58:59], v[54:55], v[244:245]
	ds_write_b64 v226, v[242:243] offset:1600
	v_cvt_pk_bf16_f32 v246, v242, v243
	ds_write_b64 v226, v[244:245] offset:2000
	v_cvt_pk_bf16_f32 v247, v244, v245
	ds_write_b32 v227, v246 offset:832
	ds_write_b32 v227, v247 offset:1040
	v_lshlrev_b32_e32 v60, 16, v72
	v_and_b32_e32 v61, 0xffff0000, v72
	v_pk_fma_f32 v[242:243], v[62:63], v[48:49], v[56:57]
	v_lshlrev_b32_e32 v62, 16, v73
	v_and_b32_e32 v63, 0xffff0000, v73
	v_pk_fma_f32 v[244:245], v[64:65], v[48:49], v[56:57]
	v_pk_fma_f32 v[242:243], v[64:65], v[50:51], v[242:243]
	v_pk_fma_f32 v[244:245], v[58:59], v[50:51], v[244:245]
	v_pk_fma_f32 v[242:243], v[58:59], v[52:53], v[242:243]
	v_pk_fma_f32 v[244:245], v[60:61], v[52:53], v[244:245]
	v_pk_fma_f32 v[242:243], v[60:61], v[54:55], v[242:243]
	v_pk_fma_f32 v[244:245], v[62:63], v[54:55], v[244:245]
	ds_write_b64 v226, v[242:243] offset:2400
	v_cvt_pk_bf16_f32 v246, v242, v243
	ds_write_b64 v226, v[244:245] offset:2800
	v_cvt_pk_bf16_f32 v247, v244, v245
	ds_write_b32 v227, v246 offset:1248
	ds_write_b32 v227, v247 offset:1456
	v_lshlrev_b32_e32 v64, 16, v74
	v_and_b32_e32 v65, 0xffff0000, v74
	v_pk_fma_f32 v[242:243], v[58:59], v[48:49], v[56:57]
	v_lshlrev_b32_e32 v58, 16, v75
	v_and_b32_e32 v59, 0xffff0000, v75
	v_pk_fma_f32 v[244:245], v[60:61], v[48:49], v[56:57]
	v_pk_fma_f32 v[242:243], v[60:61], v[50:51], v[242:243]
	v_pk_fma_f32 v[244:245], v[62:63], v[50:51], v[244:245]
	v_pk_fma_f32 v[242:243], v[62:63], v[52:53], v[242:243]
	v_pk_fma_f32 v[244:245], v[64:65], v[52:53], v[244:245]
	v_pk_fma_f32 v[242:243], v[64:65], v[54:55], v[242:243]
	v_pk_fma_f32 v[244:245], v[58:59], v[54:55], v[244:245]
	ds_write_b64 v226, v[242:243] offset:3200
	v_cvt_pk_bf16_f32 v246, v242, v243
	ds_write_b64 v226, v[244:245] offset:3600
	v_cvt_pk_bf16_f32 v247, v244, v245
	ds_write_b32 v227, v246 offset:1664
	ds_write_b32 v227, v247 offset:1872
	v_lshlrev_b32_e32 v60, 16, v76
	v_and_b32_e32 v61, 0xffff0000, v76
	v_pk_fma_f32 v[242:243], v[62:63], v[48:49], v[56:57]
	v_lshlrev_b32_e32 v62, 16, v77
	v_and_b32_e32 v63, 0xffff0000, v77
	v_pk_fma_f32 v[244:245], v[64:65], v[48:49], v[56:57]
	v_pk_fma_f32 v[242:243], v[64:65], v[50:51], v[242:243]
	v_pk_fma_f32 v[244:245], v[58:59], v[50:51], v[244:245]
	v_pk_fma_f32 v[242:243], v[58:59], v[52:53], v[242:243]
	v_pk_fma_f32 v[244:245], v[60:61], v[52:53], v[244:245]
	v_pk_fma_f32 v[242:243], v[60:61], v[54:55], v[242:243]
	v_pk_fma_f32 v[244:245], v[62:63], v[54:55], v[244:245]
	ds_write_b64 v226, v[242:243] offset:4000
	v_cvt_pk_bf16_f32 v246, v242, v243
	ds_write_b64 v226, v[244:245] offset:4400
	v_cvt_pk_bf16_f32 v247, v244, v245
	ds_write_b32 v227, v246 offset:2080
	ds_write_b32 v227, v247 offset:2288
	v_lshlrev_b32_e32 v64, 16, v78
	v_and_b32_e32 v65, 0xffff0000, v78
	v_pk_fma_f32 v[242:243], v[58:59], v[48:49], v[56:57]
	v_lshlrev_b32_e32 v58, 16, v79
	v_and_b32_e32 v59, 0xffff0000, v79
	v_pk_fma_f32 v[244:245], v[60:61], v[48:49], v[56:57]
	v_pk_fma_f32 v[242:243], v[60:61], v[50:51], v[242:243]
	v_pk_fma_f32 v[244:245], v[62:63], v[50:51], v[244:245]
	v_pk_fma_f32 v[242:243], v[62:63], v[52:53], v[242:243]
	v_pk_fma_f32 v[244:245], v[64:65], v[52:53], v[244:245]
	v_pk_fma_f32 v[242:243], v[64:65], v[54:55], v[242:243]
	v_pk_fma_f32 v[244:245], v[58:59], v[54:55], v[244:245]
	ds_write_b64 v226, v[242:243] offset:4800
	v_cvt_pk_bf16_f32 v246, v242, v243
	ds_write_b64 v226, v[244:245] offset:5200
	v_cvt_pk_bf16_f32 v247, v244, v245
	ds_write_b32 v227, v246 offset:2496
	ds_write_b32 v227, v247 offset:2704
	v_lshlrev_b32_e32 v60, 16, v80
	v_and_b32_e32 v61, 0xffff0000, v80
	v_pk_fma_f32 v[242:243], v[62:63], v[48:49], v[56:57]
	v_lshlrev_b32_e32 v62, 16, v81
	v_and_b32_e32 v63, 0xffff0000, v81
	v_pk_fma_f32 v[244:245], v[64:65], v[48:49], v[56:57]
	v_pk_fma_f32 v[242:243], v[64:65], v[50:51], v[242:243]
	v_pk_fma_f32 v[244:245], v[58:59], v[50:51], v[244:245]
	v_pk_fma_f32 v[242:243], v[58:59], v[52:53], v[242:243]
	v_pk_fma_f32 v[244:245], v[60:61], v[52:53], v[244:245]
	v_pk_fma_f32 v[242:243], v[60:61], v[54:55], v[242:243]
	v_pk_fma_f32 v[244:245], v[62:63], v[54:55], v[244:245]
	ds_write_b64 v226, v[242:243] offset:5600
	v_cvt_pk_bf16_f32 v246, v242, v243
	ds_write_b64 v226, v[244:245] offset:6000
	v_cvt_pk_bf16_f32 v247, v244, v245
	ds_write_b32 v227, v246 offset:2912
	ds_write_b32 v227, v247 offset:3120
	s_mov_b64 exec, -1
	s_waitcnt lgkmcnt(0)
	ds_read_b128 v[98:101], v228 offset:0
	ds_read_b128 v[102:105], v228 offset:64
	ds_read_b128 v[106:109], v228 offset:128
	ds_read_b128 v[162:165], v231
	s_waitcnt lgkmcnt(0)
	v_mfma_f32_16x16x32_bf16 v[134:137], v[110:113], v[98:101], 0
	v_mfma_f32_16x16x32_bf16 v[138:141], v[122:125], v[98:101], 0
	v_mfma_f32_16x16x32_bf16 v[134:137], v[114:117], v[102:105], v[134:137]
	v_mfma_f32_16x16x32_bf16 v[138:141], v[126:129], v[102:105], v[138:141]
	v_mfma_f32_16x16x32_bf16 v[134:137], v[118:121], v[106:109], v[134:137]
	v_mfma_f32_16x16x32_bf16 v[138:141], v[130:133], v[106:109], v[138:141]
	ds_read_b128 v[110:113], v229 offset:3328
	ds_read_b128 v[122:125], v229 offset:23296
	ds_read_b128 v[114:117], v229 offset:3392
	ds_read_b128 v[126:129], v229 offset:23360
	ds_read_b128 v[118:121], v229 offset:3456
	ds_read_b128 v[130:133], v229 offset:23424
	s_nop 7
	s_nop 7
	v_pk_fma_f32 v[166:167], v[134:135], s[4:5], v[150:151] op_sel_hi:[1,0,1]
	v_pk_fma_f32 v[168:169], v[136:137], s[4:5], v[152:153] op_sel_hi:[1,0,1]
	v_pk_fma_f32 v[204:205], v[138:139], s[4:5], v[154:155] op_sel_hi:[1,0,1]
	v_pk_fma_f32 v[206:207], v[140:141], s[4:5], v[156:157] op_sel_hi:[1,0,1]
	v_exp_f32_e32 v166, v166
	v_exp_f32_e32 v167, v167
	v_exp_f32_e32 v168, v168
	v_exp_f32_e32 v169, v169
	v_exp_f32_e32 v204, v204
	v_exp_f32_e32 v205, v205
	v_exp_f32_e32 v206, v206
	v_exp_f32_e32 v207, v207
	v_pk_add_f32 v[166:167], v[166:167], 1.0 op_sel_hi:[1,0]
	v_pk_add_f32 v[168:169], v[168:169], 1.0 op_sel_hi:[1,0]
	v_pk_add_f32 v[204:205], v[204:205], 1.0 op_sel_hi:[1,0]
	v_pk_add_f32 v[206:207], v[206:207], 1.0 op_sel_hi:[1,0]
	v_rcp_f32_e32 v166, v166
	v_rcp_f32_e32 v167, v167
	v_rcp_f32_e32 v168, v168
	v_rcp_f32_e32 v169, v169
	v_rcp_f32_e32 v204, v204
	v_rcp_f32_e32 v205, v205
	v_rcp_f32_e32 v206, v206
	v_rcp_f32_e32 v207, v207
	v_pk_mul_f32 v[208:209], v[158:159], v[166:167]
	v_pk_mul_f32 v[210:211], v[160:161], v[168:169]
	v_pk_mul_f32 v[204:205], v[162:163], v[204:205]
	v_pk_mul_f32 v[206:207], v[164:165], v[206:207]
	ds_read_b128 v[150:153], v230 offset:64
	ds_read_b128 v[154:157], v230 offset:448
	ds_read_b128 v[158:161], v230 offset:832
	ds_read_b128 v[162:165], v231 offset:64
	v_exp_f32_e32 v166, v208
	v_exp_f32_e32 v167, v209
	v_exp_f32_e32 v168, v210
	v_exp_f32_e32 v169, v211
	v_pk_fma_f32 v[216:217], v[208:209], s[4:5], v[248:249] op_sel:[0,1,0] op_sel_hi:[1,1,0]
	v_pk_fma_f32 v[218:219], v[210:211], s[4:5], v[248:249] op_sel:[0,1,0] op_sel_hi:[1,1,0]
	v_pk_fma_f32 v[216:217], v[208:209], v[216:217], v[248:249] op_sel:[0,0,1] op_sel_hi:[1,1,1]
	v_pk_fma_f32 v[218:219], v[210:211], v[218:219], v[248:249] op_sel:[0,0,1] op_sel_hi:[1,1,1]
	v_min3_f32 v212, v208, v209, v210
	v_pk_fma_f32 v[216:217], v[208:209], v[216:217], v[250:251] op_sel_hi:[1,1,0]
	v_pk_fma_f32 v[218:219], v[210:211], v[218:219], v[250:251] op_sel_hi:[1,1,0]
	v_min_f32_e32 v212, v212, v211
	v_pk_fma_f32 v[216:217], v[208:209], v[216:217], v[250:251] op_sel:[0,0,1] op_sel_hi:[1,1,1]
	v_pk_fma_f32 v[218:219], v[210:211], v[218:219], v[250:251] op_sel:[0,0,1] op_sel_hi:[1,1,1]
	v_cmp_nlt_f32_e32 vcc, 0xbe38aa3b, v212
	v_pk_mul_f32 v[216:217], v[216:217], v[208:209]
	v_pk_mul_f32 v[218:219], v[218:219], v[210:211]
	s_cbranch_vccnz .Lscan2_far0
.Lscan2_back0:
	v_sqrt_f32_e32 v216, v216
	v_sqrt_f32_e32 v217, v217
	v_sqrt_f32_e32 v218, v218
	v_sqrt_f32_e32 v219, v219
	v_pk_mul_f32 v[204:205], v[204:205], v[216:217]
	v_pk_mul_f32 v[206:207], v[206:207], v[218:219]
	s_waitcnt lgkmcnt(0)
	v_mfma_f32_16x16x32_bf16 v[142:145], v[110:113], v[98:101], 0
	v_mfma_f32_16x16x32_bf16 v[146:149], v[122:125], v[98:101], 0
	v_mfma_f32_16x16x32_bf16 v[142:145], v[114:117], v[102:105], v[142:145]
	v_mfma_f32_16x16x32_bf16 v[146:149], v[126:129], v[102:105], v[146:149]
	v_mfma_f32_16x16x32_bf16 v[142:145], v[118:121], v[106:109], v[142:145]
	v_mfma_f32_16x16x32_bf16 v[146:149], v[130:133], v[106:109], v[146:149]
	s_waitcnt vmcnt(25)
	s_nop 1
	v_fmac_f32_dpp v204, v204, v166 row_shr:1 row_mask:0xf bank_mask:0xf bound_ctrl:1
	v_fmac_f32_dpp v205, v205, v167 row_shr:1 row_mask:0xf bank_mask:0xf bound_ctrl:1
	v_fmac_f32_dpp v206, v206, v168 row_shr:1 row_mask:0xf bank_mask:0xf bound_ctrl:1
	v_fmac_f32_dpp v207, v207, v169 row_shr:1 row_mask:0xf bank_mask:0xf bound_ctrl:1
	v_mul_f32_dpp v166, v166, v166 row_shr:1 row_mask:0xf bank_mask:0xf
	v_mul_f32_dpp v167, v167, v167 row_shr:1 row_mask:0xf bank_mask:0xf
	v_mul_f32_dpp v168, v168, v168 row_shr:1 row_mask:0xf bank_mask:0xf
	v_mul_f32_dpp v169, v169, v169 row_shr:1 row_mask:0xf bank_mask:0xf
	v_fmac_f32_dpp v204, v204, v166 row_shr:2 row_mask:0xf bank_mask:0xf bound_ctrl:1
	v_fmac_f32_dpp v205, v205, v167 row_shr:2 row_mask:0xf bank_mask:0xf bound_ctrl:1
	v_fmac_f32_dpp v206, v206, v168 row_shr:2 row_mask:0xf bank_mask:0xf bound_ctrl:1
	v_fmac_f32_dpp v207, v207, v169 row_shr:2 row_mask:0xf bank_mask:0xf bound_ctrl:1
	v_mul_f32_dpp v166, v166, v166 row_shr:2 row_mask:0xf bank_mask:0xf
	v_mul_f32_dpp v167, v167, v167 row_shr:2 row_mask:0xf bank_mask:0xf
	v_mul_f32_dpp v168, v168, v168 row_shr:2 row_mask:0xf bank_mask:0xf
	v_mul_f32_dpp v169, v169, v169 row_shr:2 row_mask:0xf bank_mask:0xf
	v_fmac_f32_dpp v204, v204, v166 row_shr:4 row_mask:0xf bank_mask:0xf bound_ctrl:1
	v_fmac_f32_dpp v205, v205, v167 row_shr:4 row_mask:0xf bank_mask:0xf bound_ctrl:1
	v_fmac_f32_dpp v206, v206, v168 row_shr:4 row_mask:0xf bank_mask:0xf bound_ctrl:1
	v_fmac_f32_dpp v207, v207, v169 row_shr:4 row_mask:0xf bank_mask:0xf bound_ctrl:1
	v_mul_f32_dpp v166, v166, v166 row_shr:4 row_mask:0xf bank_mask:0xf
	v_mul_f32_dpp v167, v167, v167 row_shr:4 row_mask:0xf bank_mask:0xf
	v_mul_f32_dpp v168, v168, v168 row_shr:4 row_mask:0xf bank_mask:0xf
	v_mul_f32_dpp v169, v169, v169 row_shr:4 row_mask:0xf bank_mask:0xf
	v_fmac_f32_dpp v204, v204, v166 row_shr:8 row_mask:0xf bank_mask:0xf bound_ctrl:1
	v_fmac_f32_dpp v205, v205, v167 row_shr:8 row_mask:0xf bank_mask:0xf bound_ctrl:1
	v_fmac_f32_dpp v206, v206, v168 row_shr:8 row_mask:0xf bank_mask:0xf bound_ctrl:1
	v_fmac_f32_dpp v207, v207, v169 row_shr:8 row_mask:0xf bank_mask:0xf bound_ctrl:1
	v_mul_f32_dpp v166, v166, v166 row_shr:8 row_mask:0xf bank_mask:0xf
	v_mul_f32_dpp v167, v167, v167 row_shr:8 row_mask:0xf bank_mask:0xf
	v_mul_f32_dpp v168, v168, v168 row_shr:8 row_mask:0xf bank_mask:0xf
	v_mul_f32_dpp v169, v169, v169 row_shr:8 row_mask:0xf bank_mask:0xf
	v_fma_f32 v208, v166, v0, v204
	v_fma_f32 v209, v167, v1, v205
	v_fma_f32 v210, v168, v2, v206
	v_fma_f32 v211, v169, v3, v207
	v_mov_b32_dpp v0, v208 row_newbcast:15 row_mask:0xf bank_mask:0xf
	v_mov_b32_dpp v1, v209 row_newbcast:15 row_mask:0xf bank_mask:0xf
	v_mov_b32_dpp v2, v210 row_newbcast:15 row_mask:0xf bank_mask:0xf
	v_mov_b32_dpp v3, v211 row_newbcast:15 row_mask:0xf bank_mask:0xf
	s_waitcnt vmcnt(24)
	v_lshlrev_b32_e32 v212, 16, v24
	v_and_b32_e32 v213, 0xffff0000, v24
	v_lshlrev_b32_e32 v214, 16, v25
	v_and_b32_e32 v215, 0xffff0000, v25
	v_pk_mul_f32 v[216:217], v[212:213], v[212:213]
	v_pk_mul_f32 v[218:219], v[214:215], v[214:215]
	v_pk_fma_f32 v[216:217], v[216:217], v[36:37], v[36:37] op_sel:[0,0,1] op_sel_hi:[1,0,1]
	v_pk_fma_f32 v[218:219], v[218:219], v[36:37], v[36:37] op_sel:[0,0,1] op_sel_hi:[1,0,1]
	v_pk_mul_f32 v[216:217], v[212:213], v[216:217]
	v_pk_mul_f32 v[218:219], v[214:215], v[218:219]
	v_exp_f32_e32 v216, v216
	v_exp_f32_e32 v217, v217
	v_exp_f32_e32 v218, v218
	v_exp_f32_e32 v219, v219
	v_pk_add_f32 v[216:217], v[216:217], 1.0 op_sel_hi:[1,0]
	v_pk_add_f32 v[218:219], v[218:219], 1.0 op_sel_hi:[1,0]
	v_rcp_f32_e32 v216, v216
	v_rcp_f32_e32 v217, v217
	v_rcp_f32_e32 v218, v218
	v_rcp_f32_e32 v219, v219
	v_pk_mul_f32 v[216:217], v[212:213], v[216:217]
	v_pk_mul_f32 v[218:219], v[214:215], v[218:219]
	v_pk_mul_f32 v[216:217], v[216:217], v[208:209]
	v_pk_mul_f32 v[218:219], v[218:219], v[210:211]
	v_cvt_pk_bf16_f32 v242, v216, v217
	v_cvt_pk_bf16_f32 v243, v218, v219
	global_store_dwordx2 v236, v[242:243], s[100:101] offset:0
	ds_read_b128 v[110:113], v229 offset:6656
	ds_read_b128 v[122:125], v229 offset:26624
	ds_read_b128 v[114:117], v229 offset:6720
	ds_read_b128 v[126:129], v229 offset:26688
	ds_read_b128 v[118:121], v229 offset:6784
	ds_read_b128 v[130:133], v229 offset:26752
	v_pk_fma_f32 v[166:167], v[142:143], s[4:5], v[150:151] op_sel_hi:[1,0,1]
	v_pk_fma_f32 v[168:169], v[144:145], s[4:5], v[152:153] op_sel_hi:[1,0,1]
	v_pk_fma_f32 v[204:205], v[146:147], s[4:5], v[154:155] op_sel_hi:[1,0,1]
	v_pk_fma_f32 v[206:207], v[148:149], s[4:5], v[156:157] op_sel_hi:[1,0,1]
	v_exp_f32_e32 v166, v166
	v_exp_f32_e32 v167, v167
	v_exp_f32_e32 v168, v168
	v_exp_f32_e32 v169, v169
	v_exp_f32_e32 v204, v204
	v_exp_f32_e32 v205, v205
	v_exp_f32_e32 v206, v206
	v_exp_f32_e32 v207, v207
	v_pk_add_f32 v[166:167], v[166:167], 1.0 op_sel_hi:[1,0]
	v_pk_add_f32 v[168:169], v[168:169], 1.0 op_sel_hi:[1,0]
	v_pk_add_f32 v[204:205], v[204:205], 1.0 op_sel_hi:[1,0]
	v_pk_add_f32 v[206:207], v[206:207], 1.0 op_sel_hi:[1,0]
	v_rcp_f32_e32 v166, v166
	v_rcp_f32_e32 v167, v167
	v_rcp_f32_e32 v168, v168
	v_rcp_f32_e32 v169, v169
	v_rcp_f32_e32 v204, v204
	v_rcp_f32_e32 v205, v205
	v_rcp_f32_e32 v206, v206
	v_rcp_f32_e32 v207, v207
	v_pk_mul_f32 v[208:209], v[158:159], v[166:167]
	v_pk_mul_f32 v[210:211], v[160:161], v[168:169]
	v_pk_mul_f32 v[204:205], v[162:163], v[204:205]
	v_pk_mul_f32 v[206:207], v[164:165], v[206:207]
	ds_read_b128 v[150:153], v230 offset:128
	ds_read_b128 v[154:157], v230 offset:512
	ds_read_b128 v[158:161], v230 offset:896
	ds_read_b128 v[162:165], v231 offset:128
	v_exp_f32_e32 v166, v208
	v_exp_f32_e32 v167, v209
	v_exp_f32_e32 v168, v210
	v_exp_f32_e32 v169, v211
	v_pk_fma_f32 v[216:217], v[208:209], s[4:5], v[248:249] op_sel:[0,1,0] op_sel_hi:[1,1,0]
	v_pk_fma_f32 v[218:219], v[210:211], s[4:5], v[248:249] op_sel:[0,1,0] op_sel_hi:[1,1,0]
	v_pk_fma_f32 v[216:217], v[208:209], v[216:217], v[248:249] op_sel:[0,0,1] op_sel_hi:[1,1,1]
	v_pk_fma_f32 v[218:219], v[210:211], v[218:219], v[248:249] op_sel:[0,0,1] op_sel_hi:[1,1,1]
	v_min3_f32 v212, v208, v209, v210
	v_pk_fma_f32 v[216:217], v[208:209], v[216:217], v[250:251] op_sel_hi:[1,1,0]
	v_pk_fma_f32 v[218:219], v[210:211], v[218:219], v[250:251] op_sel_hi:[1,1,0]
	v_min_f32_e32 v212, v212, v211
	v_pk_fma_f32 v[216:217], v[208:209], v[216:217], v[250:251] op_sel:[0,0,1] op_sel_hi:[1,1,1]
	v_pk_fma_f32 v[218:219], v[210:211], v[218:219], v[250:251] op_sel:[0,0,1] op_sel_hi:[1,1,1]
	v_cmp_nlt_f32_e32 vcc, 0xbe38aa3b, v212
	v_pk_mul_f32 v[216:217], v[216:217], v[208:209]
	v_pk_mul_f32 v[218:219], v[218:219], v[210:211]
	s_cbranch_vccnz .Lscan2_far1
.Lscan2_back1:
	v_sqrt_f32_e32 v216, v216
	v_sqrt_f32_e32 v217, v217
	v_sqrt_f32_e32 v218, v218
	v_sqrt_f32_e32 v219, v219
	v_pk_mul_f32 v[204:205], v[204:205], v[216:217]
	v_pk_mul_f32 v[206:207], v[206:207], v[218:219]
	s_waitcnt lgkmcnt(0)
	v_mfma_f32_16x16x32_bf16 v[134:137], v[110:113], v[98:101], 0
	v_mfma_f32_16x16x32_bf16 v[138:141], v[122:125], v[98:101], 0
	v_mfma_f32_16x16x32_bf16 v[134:137], v[114:117], v[102:105], v[134:137]
	v_mfma_f32_16x16x32_bf16 v[138:141], v[126:129], v[102:105], v[138:141]
	v_mfma_f32_16x16x32_bf16 v[134:137], v[118:121], v[106:109], v[134:137]
	v_mfma_f32_16x16x32_bf16 v[138:141], v[130:133], v[106:109], v[138:141]
	s_nop 1
	v_fmac_f32_dpp v204, v204, v166 row_shr:1 row_mask:0xf bank_mask:0xf bound_ctrl:1
	v_fmac_f32_dpp v205, v205, v167 row_shr:1 row_mask:0xf bank_mask:0xf bound_ctrl:1
	v_fmac_f32_dpp v206, v206, v168 row_shr:1 row_mask:0xf bank_mask:0xf bound_ctrl:1
	v_fmac_f32_dpp v207, v207, v169 row_shr:1 row_mask:0xf bank_mask:0xf bound_ctrl:1
	v_mul_f32_dpp v166, v166, v166 row_shr:1 row_mask:0xf bank_mask:0xf
	v_mul_f32_dpp v167, v167, v167 row_shr:1 row_mask:0xf bank_mask:0xf
	v_mul_f32_dpp v168, v168, v168 row_shr:1 row_mask:0xf bank_mask:0xf
	v_mul_f32_dpp v169, v169, v169 row_shr:1 row_mask:0xf bank_mask:0xf
	v_fmac_f32_dpp v204, v204, v166 row_shr:2 row_mask:0xf bank_mask:0xf bound_ctrl:1
	v_fmac_f32_dpp v205, v205, v167 row_shr:2 row_mask:0xf bank_mask:0xf bound_ctrl:1
	v_fmac_f32_dpp v206, v206, v168 row_shr:2 row_mask:0xf bank_mask:0xf bound_ctrl:1
	v_fmac_f32_dpp v207, v207, v169 row_shr:2 row_mask:0xf bank_mask:0xf bound_ctrl:1
	v_mul_f32_dpp v166, v166, v166 row_shr:2 row_mask:0xf bank_mask:0xf
	v_mul_f32_dpp v167, v167, v167 row_shr:2 row_mask:0xf bank_mask:0xf
	v_mul_f32_dpp v168, v168, v168 row_shr:2 row_mask:0xf bank_mask:0xf
	v_mul_f32_dpp v169, v169, v169 row_shr:2 row_mask:0xf bank_mask:0xf
	v_fmac_f32_dpp v204, v204, v166 row_shr:4 row_mask:0xf bank_mask:0xf bound_ctrl:1
	v_fmac_f32_dpp v205, v205, v167 row_shr:4 row_mask:0xf bank_mask:0xf bound_ctrl:1
	v_fmac_f32_dpp v206, v206, v168 row_shr:4 row_mask:0xf bank_mask:0xf bound_ctrl:1
	v_fmac_f32_dpp v207, v207, v169 row_shr:4 row_mask:0xf bank_mask:0xf bound_ctrl:1
	v_mul_f32_dpp v166, v166, v166 row_shr:4 row_mask:0xf bank_mask:0xf
	v_mul_f32_dpp v167, v167, v167 row_shr:4 row_mask:0xf bank_mask:0xf
	v_mul_f32_dpp v168, v168, v168 row_shr:4 row_mask:0xf bank_mask:0xf
	v_mul_f32_dpp v169, v169, v169 row_shr:4 row_mask:0xf bank_mask:0xf
	v_fmac_f32_dpp v204, v204, v166 row_shr:8 row_mask:0xf bank_mask:0xf bound_ctrl:1
	v_fmac_f32_dpp v205, v205, v167 row_shr:8 row_mask:0xf bank_mask:0xf bound_ctrl:1
	v_fmac_f32_dpp v206, v206, v168 row_shr:8 row_mask:0xf bank_mask:0xf bound_ctrl:1
	v_fmac_f32_dpp v207, v207, v169 row_shr:8 row_mask:0xf bank_mask:0xf bound_ctrl:1
	v_mul_f32_dpp v166, v166, v166 row_shr:8 row_mask:0xf bank_mask:0xf
	v_mul_f32_dpp v167, v167, v167 row_shr:8 row_mask:0xf bank_mask:0xf
	v_mul_f32_dpp v168, v168, v168 row_shr:8 row_mask:0xf bank_mask:0xf
	v_mul_f32_dpp v169, v169, v169 row_shr:8 row_mask:0xf bank_mask:0xf
	v_fma_f32 v208, v166, v4, v204
	v_fma_f32 v209, v167, v5, v205
	v_fma_f32 v210, v168, v6, v206
	v_fma_f32 v211, v169, v7, v207
	v_mov_b32_dpp v4, v208 row_newbcast:15 row_mask:0xf bank_mask:0xf
	v_mov_b32_dpp v5, v209 row_newbcast:15 row_mask:0xf bank_mask:0xf
	v_mov_b32_dpp v6, v210 row_newbcast:15 row_mask:0xf bank_mask:0xf
	v_mov_b32_dpp v7, v211 row_newbcast:15 row_mask:0xf bank_mask:0xf
	s_waitcnt vmcnt(24)
	v_lshlrev_b32_e32 v212, 16, v26
	v_and_b32_e32 v213, 0xffff0000, v26
	v_lshlrev_b32_e32 v214, 16, v27
	v_and_b32_e32 v215, 0xffff0000, v27
	v_pk_mul_f32 v[216:217], v[212:213], v[212:213]
	v_pk_mul_f32 v[218:219], v[214:215], v[214:215]
	v_pk_fma_f32 v[216:217], v[216:217], v[36:37], v[36:37] op_sel:[0,0,1] op_sel_hi:[1,0,1]
	v_pk_fma_f32 v[218:219], v[218:219], v[36:37], v[36:37] op_sel:[0,0,1] op_sel_hi:[1,0,1]
	v_pk_mul_f32 v[216:217], v[212:213], v[216:217]
	v_pk_mul_f32 v[218:219], v[214:215], v[218:219]
	v_exp_f32_e32 v216, v216
	v_exp_f32_e32 v217, v217
	v_exp_f32_e32 v218, v218
	v_exp_f32_e32 v219, v219
	v_pk_add_f32 v[216:217], v[216:217], 1.0 op_sel_hi:[1,0]
	v_pk_add_f32 v[218:219], v[218:219], 1.0 op_sel_hi:[1,0]
	v_rcp_f32_e32 v216, v216
	v_rcp_f32_e32 v217, v217
	v_rcp_f32_e32 v218, v218
	v_rcp_f32_e32 v219, v219
	v_pk_mul_f32 v[216:217], v[212:213], v[216:217]
	v_pk_mul_f32 v[218:219], v[214:215], v[218:219]
	v_pk_mul_f32 v[216:217], v[216:217], v[208:209]
	v_pk_mul_f32 v[218:219], v[218:219], v[210:211]
	v_cvt_pk_bf16_f32 v242, v216, v217
	v_cvt_pk_bf16_f32 v243, v218, v219
	global_store_dwordx2 v236, v[242:243], s[100:101] offset:32
	ds_read_b128 v[110:113], v229 offset:9984
	ds_read_b128 v[122:125], v229 offset:29952
	ds_read_b128 v[114:117], v229 offset:10048
	ds_read_b128 v[126:129], v229 offset:30016
	ds_read_b128 v[118:121], v229 offset:10112
	ds_read_b128 v[130:133], v229 offset:30080
	v_pk_fma_f32 v[166:167], v[134:135], s[4:5], v[150:151] op_sel_hi:[1,0,1]
	v_pk_fma_f32 v[168:169], v[136:137], s[4:5], v[152:153] op_sel_hi:[1,0,1]
	v_pk_fma_f32 v[204:205], v[138:139], s[4:5], v[154:155] op_sel_hi:[1,0,1]
	v_pk_fma_f32 v[206:207], v[140:141], s[4:5], v[156:157] op_sel_hi:[1,0,1]
	v_exp_f32_e32 v166, v166
	v_exp_f32_e32 v167, v167
	v_exp_f32_e32 v168, v168
	v_exp_f32_e32 v169, v169
	v_exp_f32_e32 v204, v204
	v_exp_f32_e32 v205, v205
	v_exp_f32_e32 v206, v206
	v_exp_f32_e32 v207, v207
	v_pk_add_f32 v[166:167], v[166:167], 1.0 op_sel_hi:[1,0]
	v_pk_add_f32 v[168:169], v[168:169], 1.0 op_sel_hi:[1,0]
	v_pk_add_f32 v[204:205], v[204:205], 1.0 op_sel_hi:[1,0]
	v_pk_add_f32 v[206:207], v[206:207], 1.0 op_sel_hi:[1,0]
	v_rcp_f32_e32 v166, v166
	v_rcp_f32_e32 v167, v167
	v_rcp_f32_e32 v168, v168
	v_rcp_f32_e32 v169, v169
	v_rcp_f32_e32 v204, v204
	v_rcp_f32_e32 v205, v205
	v_rcp_f32_e32 v206, v206
	v_rcp_f32_e32 v207, v207
	v_pk_mul_f32 v[208:209], v[158:159], v[166:167]
	v_pk_mul_f32 v[210:211], v[160:161], v[168:169]
	v_pk_mul_f32 v[204:205], v[162:163], v[204:205]
	v_pk_mul_f32 v[206:207], v[164:165], v[206:207]
	ds_read_b128 v[150:153], v230 offset:192
	ds_read_b128 v[154:157], v230 offset:576
	ds_read_b128 v[158:161], v230 offset:960
	ds_read_b128 v[162:165], v231 offset:192
	v_exp_f32_e32 v166, v208
	v_exp_f32_e32 v167, v209
	v_exp_f32_e32 v168, v210
	v_exp_f32_e32 v169, v211
	v_pk_fma_f32 v[216:217], v[208:209], s[4:5], v[248:249] op_sel:[0,1,0] op_sel_hi:[1,1,0]
	v_pk_fma_f32 v[218:219], v[210:211], s[4:5], v[248:249] op_sel:[0,1,0] op_sel_hi:[1,1,0]
	v_pk_fma_f32 v[216:217], v[208:209], v[216:217], v[248:249] op_sel:[0,0,1] op_sel_hi:[1,1,1]
	v_pk_fma_f32 v[218:219], v[210:211], v[218:219], v[248:249] op_sel:[0,0,1] op_sel_hi:[1,1,1]
	v_min3_f32 v212, v208, v209, v210
	v_pk_fma_f32 v[216:217], v[208:209], v[216:217], v[250:251] op_sel_hi:[1,1,0]
	v_pk_fma_f32 v[218:219], v[210:211], v[218:219], v[250:251] op_sel_hi:[1,1,0]
	v_min_f32_e32 v212, v212, v211
	v_pk_fma_f32 v[216:217], v[208:209], v[216:217], v[250:251] op_sel:[0,0,1] op_sel_hi:[1,1,1]
	v_pk_fma_f32 v[218:219], v[210:211], v[218:219], v[250:251] op_sel:[0,0,1] op_sel_hi:[1,1,1]
	v_cmp_nlt_f32_e32 vcc, 0xbe38aa3b, v212
	v_pk_mul_f32 v[216:217], v[216:217], v[208:209]
	v_pk_mul_f32 v[218:219], v[218:219], v[210:211]
	s_cbranch_vccnz .Lscan2_far2
.Lscan2_back2:
	v_sqrt_f32_e32 v216, v216
	v_sqrt_f32_e32 v217, v217
	v_sqrt_f32_e32 v218, v218
	v_sqrt_f32_e32 v219, v219
	v_pk_mul_f32 v[204:205], v[204:205], v[216:217]
	v_pk_mul_f32 v[206:207], v[206:207], v[218:219]
	s_waitcnt lgkmcnt(0)
	v_mfma_f32_16x16x32_bf16 v[142:145], v[110:113], v[98:101], 0
	v_mfma_f32_16x16x32_bf16 v[146:149], v[122:125], v[98:101], 0
	v_mfma_f32_16x16x32_bf16 v[142:145], v[114:117], v[102:105], v[142:145]
	v_mfma_f32_16x16x32_bf16 v[146:149], v[126:129], v[102:105], v[146:149]
	v_mfma_f32_16x16x32_bf16 v[142:145], v[118:121], v[106:109], v[142:145]
	v_mfma_f32_16x16x32_bf16 v[146:149], v[130:133], v[106:109], v[146:149]
	s_nop 1
	v_fmac_f32_dpp v204, v204, v166 row_shr:1 row_mask:0xf bank_mask:0xf bound_ctrl:1
	v_fmac_f32_dpp v205, v205, v167 row_shr:1 row_mask:0xf bank_mask:0xf bound_ctrl:1
	v_fmac_f32_dpp v206, v206, v168 row_shr:1 row_mask:0xf bank_mask:0xf bound_ctrl:1
	v_fmac_f32_dpp v207, v207, v169 row_shr:1 row_mask:0xf bank_mask:0xf bound_ctrl:1
	v_mul_f32_dpp v166, v166, v166 row_shr:1 row_mask:0xf bank_mask:0xf
	v_mul_f32_dpp v167, v167, v167 row_shr:1 row_mask:0xf bank_mask:0xf
	v_mul_f32_dpp v168, v168, v168 row_shr:1 row_mask:0xf bank_mask:0xf
	v_mul_f32_dpp v169, v169, v169 row_shr:1 row_mask:0xf bank_mask:0xf
	v_fmac_f32_dpp v204, v204, v166 row_shr:2 row_mask:0xf bank_mask:0xf bound_ctrl:1
	v_fmac_f32_dpp v205, v205, v167 row_shr:2 row_mask:0xf bank_mask:0xf bound_ctrl:1
	v_fmac_f32_dpp v206, v206, v168 row_shr:2 row_mask:0xf bank_mask:0xf bound_ctrl:1
	v_fmac_f32_dpp v207, v207, v169 row_shr:2 row_mask:0xf bank_mask:0xf bound_ctrl:1
	v_mul_f32_dpp v166, v166, v166 row_shr:2 row_mask:0xf bank_mask:0xf
	v_mul_f32_dpp v167, v167, v167 row_shr:2 row_mask:0xf bank_mask:0xf
	v_mul_f32_dpp v168, v168, v168 row_shr:2 row_mask:0xf bank_mask:0xf
	v_mul_f32_dpp v169, v169, v169 row_shr:2 row_mask:0xf bank_mask:0xf
	v_fmac_f32_dpp v204, v204, v166 row_shr:4 row_mask:0xf bank_mask:0xf bound_ctrl:1
	v_fmac_f32_dpp v205, v205, v167 row_shr:4 row_mask:0xf bank_mask:0xf bound_ctrl:1
	v_fmac_f32_dpp v206, v206, v168 row_shr:4 row_mask:0xf bank_mask:0xf bound_ctrl:1
	v_fmac_f32_dpp v207, v207, v169 row_shr:4 row_mask:0xf bank_mask:0xf bound_ctrl:1
	v_mul_f32_dpp v166, v166, v166 row_shr:4 row_mask:0xf bank_mask:0xf
	v_mul_f32_dpp v167, v167, v167 row_shr:4 row_mask:0xf bank_mask:0xf
	v_mul_f32_dpp v168, v168, v168 row_shr:4 row_mask:0xf bank_mask:0xf
	v_mul_f32_dpp v169, v169, v169 row_shr:4 row_mask:0xf bank_mask:0xf
	v_fmac_f32_dpp v204, v204, v166 row_shr:8 row_mask:0xf bank_mask:0xf bound_ctrl:1
	v_fmac_f32_dpp v205, v205, v167 row_shr:8 row_mask:0xf bank_mask:0xf bound_ctrl:1
	v_fmac_f32_dpp v206, v206, v168 row_shr:8 row_mask:0xf bank_mask:0xf bound_ctrl:1
	v_fmac_f32_dpp v207, v207, v169 row_shr:8 row_mask:0xf bank_mask:0xf bound_ctrl:1
	v_mul_f32_dpp v166, v166, v166 row_shr:8 row_mask:0xf bank_mask:0xf
	v_mul_f32_dpp v167, v167, v167 row_shr:8 row_mask:0xf bank_mask:0xf
	v_mul_f32_dpp v168, v168, v168 row_shr:8 row_mask:0xf bank_mask:0xf
	v_mul_f32_dpp v169, v169, v169 row_shr:8 row_mask:0xf bank_mask:0xf
	v_fma_f32 v208, v166, v8, v204
	v_fma_f32 v209, v167, v9, v205
	v_fma_f32 v210, v168, v10, v206
	v_fma_f32 v211, v169, v11, v207
	v_mov_b32_dpp v8, v208 row_newbcast:15 row_mask:0xf bank_mask:0xf
	v_mov_b32_dpp v9, v209 row_newbcast:15 row_mask:0xf bank_mask:0xf
	v_mov_b32_dpp v10, v210 row_newbcast:15 row_mask:0xf bank_mask:0xf
	v_mov_b32_dpp v11, v211 row_newbcast:15 row_mask:0xf bank_mask:0xf
	s_waitcnt vmcnt(24)
	v_lshlrev_b32_e32 v212, 16, v28
	v_and_b32_e32 v213, 0xffff0000, v28
	v_lshlrev_b32_e32 v214, 16, v29
	v_and_b32_e32 v215, 0xffff0000, v29
	v_pk_mul_f32 v[216:217], v[212:213], v[212:213]
	v_pk_mul_f32 v[218:219], v[214:215], v[214:215]
	v_pk_fma_f32 v[216:217], v[216:217], v[36:37], v[36:37] op_sel:[0,0,1] op_sel_hi:[1,0,1]
	v_pk_fma_f32 v[218:219], v[218:219], v[36:37], v[36:37] op_sel:[0,0,1] op_sel_hi:[1,0,1]
	v_pk_mul_f32 v[216:217], v[212:213], v[216:217]
	v_pk_mul_f32 v[218:219], v[214:215], v[218:219]
	v_exp_f32_e32 v216, v216
	v_exp_f32_e32 v217, v217
	v_exp_f32_e32 v218, v218
	v_exp_f32_e32 v219, v219
	v_pk_add_f32 v[216:217], v[216:217], 1.0 op_sel_hi:[1,0]
	v_pk_add_f32 v[218:219], v[218:219], 1.0 op_sel_hi:[1,0]
	v_rcp_f32_e32 v216, v216
	v_rcp_f32_e32 v217, v217
	v_rcp_f32_e32 v218, v218
	v_rcp_f32_e32 v219, v219
	v_pk_mul_f32 v[216:217], v[212:213], v[216:217]
	v_pk_mul_f32 v[218:219], v[214:215], v[218:219]
	v_pk_mul_f32 v[216:217], v[216:217], v[208:209]
	v_pk_mul_f32 v[218:219], v[218:219], v[210:211]
	v_cvt_pk_bf16_f32 v242, v216, v217
	v_cvt_pk_bf16_f32 v243, v218, v219
	global_store_dwordx2 v236, v[242:243], s[100:101] offset:64
	ds_read_b128 v[110:113], v229 offset:13312
	ds_read_b128 v[122:125], v229 offset:33280
	ds_read_b128 v[114:117], v229 offset:13376
	ds_read_b128 v[126:129], v229 offset:33344
	ds_read_b128 v[118:121], v229 offset:13440
	ds_read_b128 v[130:133], v229 offset:33408
	v_pk_fma_f32 v[166:167], v[142:143], s[4:5], v[150:151] op_sel_hi:[1,0,1]
	v_pk_fma_f32 v[168:169], v[144:145], s[4:5], v[152:153] op_sel_hi:[1,0,1]
	v_pk_fma_f32 v[204:205], v[146:147], s[4:5], v[154:155] op_sel_hi:[1,0,1]
	v_pk_fma_f32 v[206:207], v[148:149], s[4:5], v[156:157] op_sel_hi:[1,0,1]
	v_exp_f32_e32 v166, v166
	v_exp_f32_e32 v167, v167
	v_exp_f32_e32 v168, v168
	v_exp_f32_e32 v169, v169
	v_exp_f32_e32 v204, v204
	v_exp_f32_e32 v205, v205
	v_exp_f32_e32 v206, v206
	v_exp_f32_e32 v207, v207
	v_pk_add_f32 v[166:167], v[166:167], 1.0 op_sel_hi:[1,0]
	v_pk_add_f32 v[168:169], v[168:169], 1.0 op_sel_hi:[1,0]
	v_pk_add_f32 v[204:205], v[204:205], 1.0 op_sel_hi:[1,0]
	v_pk_add_f32 v[206:207], v[206:207], 1.0 op_sel_hi:[1,0]
	v_rcp_f32_e32 v166, v166
	v_rcp_f32_e32 v167, v167
	v_rcp_f32_e32 v168, v168
	v_rcp_f32_e32 v169, v169
	v_rcp_f32_e32 v204, v204
	v_rcp_f32_e32 v205, v205
	v_rcp_f32_e32 v206, v206
	v_rcp_f32_e32 v207, v207
	v_pk_mul_f32 v[208:209], v[158:159], v[166:167]
	v_pk_mul_f32 v[210:211], v[160:161], v[168:169]
	v_pk_mul_f32 v[204:205], v[162:163], v[204:205]
	v_pk_mul_f32 v[206:207], v[164:165], v[206:207]
	ds_read_b128 v[150:153], v230 offset:256
	ds_read_b128 v[154:157], v230 offset:640
	ds_read_b128 v[158:161], v230 offset:1024
	ds_read_b128 v[162:165], v231 offset:256
	v_exp_f32_e32 v166, v208
	v_exp_f32_e32 v167, v209
	v_exp_f32_e32 v168, v210
	v_exp_f32_e32 v169, v211
	v_pk_fma_f32 v[216:217], v[208:209], s[4:5], v[248:249] op_sel:[0,1,0] op_sel_hi:[1,1,0]
	v_pk_fma_f32 v[218:219], v[210:211], s[4:5], v[248:249] op_sel:[0,1,0] op_sel_hi:[1,1,0]
	v_pk_fma_f32 v[216:217], v[208:209], v[216:217], v[248:249] op_sel:[0,0,1] op_sel_hi:[1,1,1]
	v_pk_fma_f32 v[218:219], v[210:211], v[218:219], v[248:249] op_sel:[0,0,1] op_sel_hi:[1,1,1]
	v_min3_f32 v212, v208, v209, v210
	v_pk_fma_f32 v[216:217], v[208:209], v[216:217], v[250:251] op_sel_hi:[1,1,0]
	v_pk_fma_f32 v[218:219], v[210:211], v[218:219], v[250:251] op_sel_hi:[1,1,0]
	v_min_f32_e32 v212, v212, v211
	v_pk_fma_f32 v[216:217], v[208:209], v[216:217], v[250:251] op_sel:[0,0,1] op_sel_hi:[1,1,1]
	v_pk_fma_f32 v[218:219], v[210:211], v[218:219], v[250:251] op_sel:[0,0,1] op_sel_hi:[1,1,1]
	v_cmp_nlt_f32_e32 vcc, 0xbe38aa3b, v212
	v_pk_mul_f32 v[216:217], v[216:217], v[208:209]
	v_pk_mul_f32 v[218:219], v[218:219], v[210:211]
	s_cbranch_vccnz .Lscan2_far3
.Lscan2_back3:
	v_sqrt_f32_e32 v216, v216
	v_sqrt_f32_e32 v217, v217
	v_sqrt_f32_e32 v218, v218
	v_sqrt_f32_e32 v219, v219
	v_pk_mul_f32 v[204:205], v[204:205], v[216:217]
	v_pk_mul_f32 v[206:207], v[206:207], v[218:219]
	s_waitcnt lgkmcnt(0)
	v_mfma_f32_16x16x32_bf16 v[134:137], v[110:113], v[98:101], 0
	v_mfma_f32_16x16x32_bf16 v[138:141], v[122:125], v[98:101], 0
	v_mfma_f32_16x16x32_bf16 v[134:137], v[114:117], v[102:105], v[134:137]
	v_mfma_f32_16x16x32_bf16 v[138:141], v[126:129], v[102:105], v[138:141]
	v_mfma_f32_16x16x32_bf16 v[134:137], v[118:121], v[106:109], v[134:137]
	v_mfma_f32_16x16x32_bf16 v[138:141], v[130:133], v[106:109], v[138:141]
	s_nop 1
	v_fmac_f32_dpp v204, v204, v166 row_shr:1 row_mask:0xf bank_mask:0xf bound_ctrl:1
	v_fmac_f32_dpp v205, v205, v167 row_shr:1 row_mask:0xf bank_mask:0xf bound_ctrl:1
	v_fmac_f32_dpp v206, v206, v168 row_shr:1 row_mask:0xf bank_mask:0xf bound_ctrl:1
	v_fmac_f32_dpp v207, v207, v169 row_shr:1 row_mask:0xf bank_mask:0xf bound_ctrl:1
	v_mul_f32_dpp v166, v166, v166 row_shr:1 row_mask:0xf bank_mask:0xf
	v_mul_f32_dpp v167, v167, v167 row_shr:1 row_mask:0xf bank_mask:0xf
	v_mul_f32_dpp v168, v168, v168 row_shr:1 row_mask:0xf bank_mask:0xf
	v_mul_f32_dpp v169, v169, v169 row_shr:1 row_mask:0xf bank_mask:0xf
	v_fmac_f32_dpp v204, v204, v166 row_shr:2 row_mask:0xf bank_mask:0xf bound_ctrl:1
	v_fmac_f32_dpp v205, v205, v167 row_shr:2 row_mask:0xf bank_mask:0xf bound_ctrl:1
	v_fmac_f32_dpp v206, v206, v168 row_shr:2 row_mask:0xf bank_mask:0xf bound_ctrl:1
	v_fmac_f32_dpp v207, v207, v169 row_shr:2 row_mask:0xf bank_mask:0xf bound_ctrl:1
	v_mul_f32_dpp v166, v166, v166 row_shr:2 row_mask:0xf bank_mask:0xf
	v_mul_f32_dpp v167, v167, v167 row_shr:2 row_mask:0xf bank_mask:0xf
	v_mul_f32_dpp v168, v168, v168 row_shr:2 row_mask:0xf bank_mask:0xf
	v_mul_f32_dpp v169, v169, v169 row_shr:2 row_mask:0xf bank_mask:0xf
	v_fmac_f32_dpp v204, v204, v166 row_shr:4 row_mask:0xf bank_mask:0xf bound_ctrl:1
	v_fmac_f32_dpp v205, v205, v167 row_shr:4 row_mask:0xf bank_mask:0xf bound_ctrl:1
	v_fmac_f32_dpp v206, v206, v168 row_shr:4 row_mask:0xf bank_mask:0xf bound_ctrl:1
	v_fmac_f32_dpp v207, v207, v169 row_shr:4 row_mask:0xf bank_mask:0xf bound_ctrl:1
	v_mul_f32_dpp v166, v166, v166 row_shr:4 row_mask:0xf bank_mask:0xf
	v_mul_f32_dpp v167, v167, v167 row_shr:4 row_mask:0xf bank_mask:0xf
	v_mul_f32_dpp v168, v168, v168 row_shr:4 row_mask:0xf bank_mask:0xf
	v_mul_f32_dpp v169, v169, v169 row_shr:4 row_mask:0xf bank_mask:0xf
	v_fmac_f32_dpp v204, v204, v166 row_shr:8 row_mask:0xf bank_mask:0xf bound_ctrl:1
	v_fmac_f32_dpp v205, v205, v167 row_shr:8 row_mask:0xf bank_mask:0xf bound_ctrl:1
	v_fmac_f32_dpp v206, v206, v168 row_shr:8 row_mask:0xf bank_mask:0xf bound_ctrl:1
	v_fmac_f32_dpp v207, v207, v169 row_shr:8 row_mask:0xf bank_mask:0xf bound_ctrl:1
	v_mul_f32_dpp v166, v166, v166 row_shr:8 row_mask:0xf bank_mask:0xf
	v_mul_f32_dpp v167, v167, v167 row_shr:8 row_mask:0xf bank_mask:0xf
	v_mul_f32_dpp v168, v168, v168 row_shr:8 row_mask:0xf bank_mask:0xf
	v_mul_f32_dpp v169, v169, v169 row_shr:8 row_mask:0xf bank_mask:0xf
	v_fma_f32 v208, v166, v12, v204
	v_fma_f32 v209, v167, v13, v205
	v_fma_f32 v210, v168, v14, v206
	v_fma_f32 v211, v169, v15, v207
	v_mov_b32_dpp v12, v208 row_newbcast:15 row_mask:0xf bank_mask:0xf
	v_mov_b32_dpp v13, v209 row_newbcast:15 row_mask:0xf bank_mask:0xf
	v_mov_b32_dpp v14, v210 row_newbcast:15 row_mask:0xf bank_mask:0xf
	v_mov_b32_dpp v15, v211 row_newbcast:15 row_mask:0xf bank_mask:0xf
	s_waitcnt vmcnt(24)
	v_lshlrev_b32_e32 v212, 16, v30
	v_and_b32_e32 v213, 0xffff0000, v30
	v_lshlrev_b32_e32 v214, 16, v31
	v_and_b32_e32 v215, 0xffff0000, v31
	v_pk_mul_f32 v[216:217], v[212:213], v[212:213]
	v_pk_mul_f32 v[218:219], v[214:215], v[214:215]
	v_pk_fma_f32 v[216:217], v[216:217], v[36:37], v[36:37] op_sel:[0,0,1] op_sel_hi:[1,0,1]
	v_pk_fma_f32 v[218:219], v[218:219], v[36:37], v[36:37] op_sel:[0,0,1] op_sel_hi:[1,0,1]
	v_pk_mul_f32 v[216:217], v[212:213], v[216:217]
	v_pk_mul_f32 v[218:219], v[214:215], v[218:219]
	v_exp_f32_e32 v216, v216
	v_exp_f32_e32 v217, v217
	v_exp_f32_e32 v218, v218
	v_exp_f32_e32 v219, v219
	v_pk_add_f32 v[216:217], v[216:217], 1.0 op_sel_hi:[1,0]
	v_pk_add_f32 v[218:219], v[218:219], 1.0 op_sel_hi:[1,0]
	v_rcp_f32_e32 v216, v216
	v_rcp_f32_e32 v217, v217
	v_rcp_f32_e32 v218, v218
	v_rcp_f32_e32 v219, v219
	v_pk_mul_f32 v[216:217], v[212:213], v[216:217]
	v_pk_mul_f32 v[218:219], v[214:215], v[218:219]
	v_pk_mul_f32 v[216:217], v[216:217], v[208:209]
	v_pk_mul_f32 v[218:219], v[218:219], v[210:211]
	v_cvt_pk_bf16_f32 v242, v216, v217
	v_cvt_pk_bf16_f32 v243, v218, v219
	global_store_dwordx2 v236, v[242:243], s[100:101] offset:96
	ds_read_b128 v[110:113], v229 offset:16640
	ds_read_b128 v[122:125], v229 offset:36608
	ds_read_b128 v[114:117], v229 offset:16704
	ds_read_b128 v[126:129], v229 offset:36672
	ds_read_b128 v[118:121], v229 offset:16768
	ds_read_b128 v[130:133], v229 offset:36736
	v_pk_fma_f32 v[166:167], v[134:135], s[4:5], v[150:151] op_sel_hi:[1,0,1]
	v_pk_fma_f32 v[168:169], v[136:137], s[4:5], v[152:153] op_sel_hi:[1,0,1]
	v_pk_fma_f32 v[204:205], v[138:139], s[4:5], v[154:155] op_sel_hi:[1,0,1]
	v_pk_fma_f32 v[206:207], v[140:141], s[4:5], v[156:157] op_sel_hi:[1,0,1]
	v_exp_f32_e32 v166, v166
	v_exp_f32_e32 v167, v167
	v_exp_f32_e32 v168, v168
	v_exp_f32_e32 v169, v169
	v_exp_f32_e32 v204, v204
	v_exp_f32_e32 v205, v205
	v_exp_f32_e32 v206, v206
	v_exp_f32_e32 v207, v207
	v_pk_add_f32 v[166:167], v[166:167], 1.0 op_sel_hi:[1,0]
	v_pk_add_f32 v[168:169], v[168:169], 1.0 op_sel_hi:[1,0]
	v_pk_add_f32 v[204:205], v[204:205], 1.0 op_sel_hi:[1,0]
	v_pk_add_f32 v[206:207], v[206:207], 1.0 op_sel_hi:[1,0]
	v_rcp_f32_e32 v166, v166
	v_rcp_f32_e32 v167, v167
	v_rcp_f32_e32 v168, v168
	v_rcp_f32_e32 v169, v169
	v_rcp_f32_e32 v204, v204
	v_rcp_f32_e32 v205, v205
	v_rcp_f32_e32 v206, v206
	v_rcp_f32_e32 v207, v207
	v_pk_mul_f32 v[208:209], v[158:159], v[166:167]
	v_pk_mul_f32 v[210:211], v[160:161], v[168:169]
	v_pk_mul_f32 v[204:205], v[162:163], v[204:205]
	v_pk_mul_f32 v[206:207], v[164:165], v[206:207]
	ds_read_b128 v[150:153], v230 offset:320
	ds_read_b128 v[154:157], v230 offset:704
	ds_read_b128 v[158:161], v230 offset:1088
	ds_read_b128 v[162:165], v231 offset:320
	v_exp_f32_e32 v166, v208
	v_exp_f32_e32 v167, v209
	v_exp_f32_e32 v168, v210
	v_exp_f32_e32 v169, v211
	v_pk_fma_f32 v[216:217], v[208:209], s[4:5], v[248:249] op_sel:[0,1,0] op_sel_hi:[1,1,0]
	v_pk_fma_f32 v[218:219], v[210:211], s[4:5], v[248:249] op_sel:[0,1,0] op_sel_hi:[1,1,0]
	v_pk_fma_f32 v[216:217], v[208:209], v[216:217], v[248:249] op_sel:[0,0,1] op_sel_hi:[1,1,1]
	v_pk_fma_f32 v[218:219], v[210:211], v[218:219], v[248:249] op_sel:[0,0,1] op_sel_hi:[1,1,1]
	v_min3_f32 v212, v208, v209, v210
	v_pk_fma_f32 v[216:217], v[208:209], v[216:217], v[250:251] op_sel_hi:[1,1,0]
	v_pk_fma_f32 v[218:219], v[210:211], v[218:219], v[250:251] op_sel_hi:[1,1,0]
	v_min_f32_e32 v212, v212, v211
	v_pk_fma_f32 v[216:217], v[208:209], v[216:217], v[250:251] op_sel:[0,0,1] op_sel_hi:[1,1,1]
	v_pk_fma_f32 v[218:219], v[210:211], v[218:219], v[250:251] op_sel:[0,0,1] op_sel_hi:[1,1,1]
	v_cmp_nlt_f32_e32 vcc, 0xbe38aa3b, v212
	v_pk_mul_f32 v[216:217], v[216:217], v[208:209]
	v_pk_mul_f32 v[218:219], v[218:219], v[210:211]
	s_cbranch_vccnz .Lscan2_far4
.Lscan2_back4:
	v_sqrt_f32_e32 v216, v216
	v_sqrt_f32_e32 v217, v217
	v_sqrt_f32_e32 v218, v218
	v_sqrt_f32_e32 v219, v219
	v_pk_mul_f32 v[204:205], v[204:205], v[216:217]
	v_pk_mul_f32 v[206:207], v[206:207], v[218:219]
	s_waitcnt lgkmcnt(0)
	v_mfma_f32_16x16x32_bf16 v[142:145], v[110:113], v[98:101], 0
	v_mfma_f32_16x16x32_bf16 v[146:149], v[122:125], v[98:101], 0
	v_mfma_f32_16x16x32_bf16 v[142:145], v[114:117], v[102:105], v[142:145]
	v_mfma_f32_16x16x32_bf16 v[146:149], v[126:129], v[102:105], v[146:149]
	v_mfma_f32_16x16x32_bf16 v[142:145], v[118:121], v[106:109], v[142:145]
	v_mfma_f32_16x16x32_bf16 v[146:149], v[130:133], v[106:109], v[146:149]
	s_nop 1
	v_fmac_f32_dpp v204, v204, v166 row_shr:1 row_mask:0xf bank_mask:0xf bound_ctrl:1
	v_fmac_f32_dpp v205, v205, v167 row_shr:1 row_mask:0xf bank_mask:0xf bound_ctrl:1
	v_fmac_f32_dpp v206, v206, v168 row_shr:1 row_mask:0xf bank_mask:0xf bound_ctrl:1
	v_fmac_f32_dpp v207, v207, v169 row_shr:1 row_mask:0xf bank_mask:0xf bound_ctrl:1
	v_mul_f32_dpp v166, v166, v166 row_shr:1 row_mask:0xf bank_mask:0xf
	v_mul_f32_dpp v167, v167, v167 row_shr:1 row_mask:0xf bank_mask:0xf
	v_mul_f32_dpp v168, v168, v168 row_shr:1 row_mask:0xf bank_mask:0xf
	v_mul_f32_dpp v169, v169, v169 row_shr:1 row_mask:0xf bank_mask:0xf
	v_fmac_f32_dpp v204, v204, v166 row_shr:2 row_mask:0xf bank_mask:0xf bound_ctrl:1
	v_fmac_f32_dpp v205, v205, v167 row_shr:2 row_mask:0xf bank_mask:0xf bound_ctrl:1
	v_fmac_f32_dpp v206, v206, v168 row_shr:2 row_mask:0xf bank_mask:0xf bound_ctrl:1
	v_fmac_f32_dpp v207, v207, v169 row_shr:2 row_mask:0xf bank_mask:0xf bound_ctrl:1
	v_mul_f32_dpp v166, v166, v166 row_shr:2 row_mask:0xf bank_mask:0xf
	v_mul_f32_dpp v167, v167, v167 row_shr:2 row_mask:0xf bank_mask:0xf
	v_mul_f32_dpp v168, v168, v168 row_shr:2 row_mask:0xf bank_mask:0xf
	v_mul_f32_dpp v169, v169, v169 row_shr:2 row_mask:0xf bank_mask:0xf
	v_fmac_f32_dpp v204, v204, v166 row_shr:4 row_mask:0xf bank_mask:0xf bound_ctrl:1
	v_fmac_f32_dpp v205, v205, v167 row_shr:4 row_mask:0xf bank_mask:0xf bound_ctrl:1
	v_fmac_f32_dpp v206, v206, v168 row_shr:4 row_mask:0xf bank_mask:0xf bound_ctrl:1
	v_fmac_f32_dpp v207, v207, v169 row_shr:4 row_mask:0xf bank_mask:0xf bound_ctrl:1
	v_mul_f32_dpp v166, v166, v166 row_shr:4 row_mask:0xf bank_mask:0xf
	v_mul_f32_dpp v167, v167, v167 row_shr:4 row_mask:0xf bank_mask:0xf
	v_mul_f32_dpp v168, v168, v168 row_shr:4 row_mask:0xf bank_mask:0xf
	v_mul_f32_dpp v169, v169, v169 row_shr:4 row_mask:0xf bank_mask:0xf
	v_fmac_f32_dpp v204, v204, v166 row_shr:8 row_mask:0xf bank_mask:0xf bound_ctrl:1
	v_fmac_f32_dpp v205, v205, v167 row_shr:8 row_mask:0xf bank_mask:0xf bound_ctrl:1
	v_fmac_f32_dpp v206, v206, v168 row_shr:8 row_mask:0xf bank_mask:0xf bound_ctrl:1
	v_fmac_f32_dpp v207, v207, v169 row_shr:8 row_mask:0xf bank_mask:0xf bound_ctrl:1
	v_mul_f32_dpp v166, v166, v166 row_shr:8 row_mask:0xf bank_mask:0xf
	v_mul_f32_dpp v167, v167, v167 row_shr:8 row_mask:0xf bank_mask:0xf
	v_mul_f32_dpp v168, v168, v168 row_shr:8 row_mask:0xf bank_mask:0xf
	v_mul_f32_dpp v169, v169, v169 row_shr:8 row_mask:0xf bank_mask:0xf
	v_fma_f32 v208, v166, v16, v204
	v_fma_f32 v209, v167, v17, v205
	v_fma_f32 v210, v168, v18, v206
	v_fma_f32 v211, v169, v19, v207
	v_mov_b32_dpp v16, v208 row_newbcast:15 row_mask:0xf bank_mask:0xf
	v_mov_b32_dpp v17, v209 row_newbcast:15 row_mask:0xf bank_mask:0xf
	v_mov_b32_dpp v18, v210 row_newbcast:15 row_mask:0xf bank_mask:0xf
	v_mov_b32_dpp v19, v211 row_newbcast:15 row_mask:0xf bank_mask:0xf
	s_waitcnt vmcnt(24)
	v_lshlrev_b32_e32 v212, 16, v32
	v_and_b32_e32 v213, 0xffff0000, v32
	v_lshlrev_b32_e32 v214, 16, v33
	v_and_b32_e32 v215, 0xffff0000, v33
	v_pk_mul_f32 v[216:217], v[212:213], v[212:213]
	v_pk_mul_f32 v[218:219], v[214:215], v[214:215]
	v_pk_fma_f32 v[216:217], v[216:217], v[36:37], v[36:37] op_sel:[0,0,1] op_sel_hi:[1,0,1]
	v_pk_fma_f32 v[218:219], v[218:219], v[36:37], v[36:37] op_sel:[0,0,1] op_sel_hi:[1,0,1]
	v_pk_mul_f32 v[216:217], v[212:213], v[216:217]
	v_pk_mul_f32 v[218:219], v[214:215], v[218:219]
	v_exp_f32_e32 v216, v216
	v_exp_f32_e32 v217, v217
	v_exp_f32_e32 v218, v218
	v_exp_f32_e32 v219, v219
	v_pk_add_f32 v[216:217], v[216:217], 1.0 op_sel_hi:[1,0]
	v_pk_add_f32 v[218:219], v[218:219], 1.0 op_sel_hi:[1,0]
	v_rcp_f32_e32 v216, v216
	v_rcp_f32_e32 v217, v217
	v_rcp_f32_e32 v218, v218
	v_rcp_f32_e32 v219, v219
	v_pk_mul_f32 v[216:217], v[212:213], v[216:217]
	v_pk_mul_f32 v[218:219], v[214:215], v[218:219]
	v_pk_mul_f32 v[216:217], v[216:217], v[208:209]
	v_pk_mul_f32 v[218:219], v[218:219], v[210:211]
	v_cvt_pk_bf16_f32 v242, v216, v217
	v_cvt_pk_bf16_f32 v243, v218, v219
	global_store_dwordx2 v236, v[242:243], s[100:101] offset:128
	v_pk_fma_f32 v[166:167], v[142:143], s[4:5], v[150:151] op_sel_hi:[1,0,1]
	v_pk_fma_f32 v[168:169], v[144:145], s[4:5], v[152:153] op_sel_hi:[1,0,1]
	v_pk_fma_f32 v[204:205], v[146:147], s[4:5], v[154:155] op_sel_hi:[1,0,1]
	v_pk_fma_f32 v[206:207], v[148:149], s[4:5], v[156:157] op_sel_hi:[1,0,1]
	v_exp_f32_e32 v166, v166
	v_exp_f32_e32 v167, v167
	v_exp_f32_e32 v168, v168
	v_exp_f32_e32 v169, v169
	v_exp_f32_e32 v204, v204
	v_exp_f32_e32 v205, v205
	v_exp_f32_e32 v206, v206
	v_exp_f32_e32 v207, v207
	v_pk_add_f32 v[166:167], v[166:167], 1.0 op_sel_hi:[1,0]
	v_pk_add_f32 v[168:169], v[168:169], 1.0 op_sel_hi:[1,0]
	v_pk_add_f32 v[204:205], v[204:205], 1.0 op_sel_hi:[1,0]
	v_pk_add_f32 v[206:207], v[206:207], 1.0 op_sel_hi:[1,0]
	v_rcp_f32_e32 v166, v166
	v_rcp_f32_e32 v167, v167
	v_rcp_f32_e32 v168, v168
	v_rcp_f32_e32 v169, v169
	v_rcp_f32_e32 v204, v204
	v_rcp_f32_e32 v205, v205
	v_rcp_f32_e32 v206, v206
	v_rcp_f32_e32 v207, v207
	v_pk_mul_f32 v[208:209], v[158:159], v[166:167]
	v_pk_mul_f32 v[210:211], v[160:161], v[168:169]
	v_pk_mul_f32 v[204:205], v[162:163], v[204:205]
	v_pk_mul_f32 v[206:207], v[164:165], v[206:207]
	v_exp_f32_e32 v166, v208
	v_exp_f32_e32 v167, v209
	v_exp_f32_e32 v168, v210
	v_exp_f32_e32 v169, v211
	v_pk_fma_f32 v[216:217], v[208:209], s[4:5], v[248:249] op_sel:[0,1,0] op_sel_hi:[1,1,0]
	v_pk_fma_f32 v[218:219], v[210:211], s[4:5], v[248:249] op_sel:[0,1,0] op_sel_hi:[1,1,0]
	v_pk_fma_f32 v[216:217], v[208:209], v[216:217], v[248:249] op_sel:[0,0,1] op_sel_hi:[1,1,1]
	v_pk_fma_f32 v[218:219], v[210:211], v[218:219], v[248:249] op_sel:[0,0,1] op_sel_hi:[1,1,1]
	v_min3_f32 v212, v208, v209, v210
	v_pk_fma_f32 v[216:217], v[208:209], v[216:217], v[250:251] op_sel_hi:[1,1,0]
	v_pk_fma_f32 v[218:219], v[210:211], v[218:219], v[250:251] op_sel_hi:[1,1,0]
	v_min_f32_e32 v212, v212, v211
	v_pk_fma_f32 v[216:217], v[208:209], v[216:217], v[250:251] op_sel:[0,0,1] op_sel_hi:[1,1,1]
	v_pk_fma_f32 v[218:219], v[210:211], v[218:219], v[250:251] op_sel:[0,0,1] op_sel_hi:[1,1,1]
	v_cmp_nlt_f32_e32 vcc, 0xbe38aa3b, v212
	v_pk_mul_f32 v[216:217], v[216:217], v[208:209]
	v_pk_mul_f32 v[218:219], v[218:219], v[210:211]
	s_cbranch_vccnz .Lscan2_far5
.Lscan2_back5:
	v_sqrt_f32_e32 v216, v216
	v_sqrt_f32_e32 v217, v217
	v_sqrt_f32_e32 v218, v218
	v_sqrt_f32_e32 v219, v219
	v_pk_mul_f32 v[204:205], v[204:205], v[216:217]
	v_pk_mul_f32 v[206:207], v[206:207], v[218:219]
	s_waitcnt lgkmcnt(0)
	s_nop 1
	v_fmac_f32_dpp v204, v204, v166 row_shr:1 row_mask:0xf bank_mask:0xf bound_ctrl:1
	v_fmac_f32_dpp v205, v205, v167 row_shr:1 row_mask:0xf bank_mask:0xf bound_ctrl:1
	v_fmac_f32_dpp v206, v206, v168 row_shr:1 row_mask:0xf bank_mask:0xf bound_ctrl:1
	v_fmac_f32_dpp v207, v207, v169 row_shr:1 row_mask:0xf bank_mask:0xf bound_ctrl:1
	v_mul_f32_dpp v166, v166, v166 row_shr:1 row_mask:0xf bank_mask:0xf
	v_mul_f32_dpp v167, v167, v167 row_shr:1 row_mask:0xf bank_mask:0xf
	v_mul_f32_dpp v168, v168, v168 row_shr:1 row_mask:0xf bank_mask:0xf
	v_mul_f32_dpp v169, v169, v169 row_shr:1 row_mask:0xf bank_mask:0xf
	v_fmac_f32_dpp v204, v204, v166 row_shr:2 row_mask:0xf bank_mask:0xf bound_ctrl:1
	v_fmac_f32_dpp v205, v205, v167 row_shr:2 row_mask:0xf bank_mask:0xf bound_ctrl:1
	v_fmac_f32_dpp v206, v206, v168 row_shr:2 row_mask:0xf bank_mask:0xf bound_ctrl:1
	v_fmac_f32_dpp v207, v207, v169 row_shr:2 row_mask:0xf bank_mask:0xf bound_ctrl:1
	v_mul_f32_dpp v166, v166, v166 row_shr:2 row_mask:0xf bank_mask:0xf
	v_mul_f32_dpp v167, v167, v167 row_shr:2 row_mask:0xf bank_mask:0xf
	v_mul_f32_dpp v168, v168, v168 row_shr:2 row_mask:0xf bank_mask:0xf
	v_mul_f32_dpp v169, v169, v169 row_shr:2 row_mask:0xf bank_mask:0xf
	v_fmac_f32_dpp v204, v204, v166 row_shr:4 row_mask:0xf bank_mask:0xf bound_ctrl:1
	v_fmac_f32_dpp v205, v205, v167 row_shr:4 row_mask:0xf bank_mask:0xf bound_ctrl:1
	v_fmac_f32_dpp v206, v206, v168 row_shr:4 row_mask:0xf bank_mask:0xf bound_ctrl:1
	v_fmac_f32_dpp v207, v207, v169 row_shr:4 row_mask:0xf bank_mask:0xf bound_ctrl:1
	v_mul_f32_dpp v166, v166, v166 row_shr:4 row_mask:0xf bank_mask:0xf
	v_mul_f32_dpp v167, v167, v167 row_shr:4 row_mask:0xf bank_mask:0xf
	v_mul_f32_dpp v168, v168, v168 row_shr:4 row_mask:0xf bank_mask:0xf
	v_mul_f32_dpp v169, v169, v169 row_shr:4 row_mask:0xf bank_mask:0xf
	v_fmac_f32_dpp v204, v204, v166 row_shr:8 row_mask:0xf bank_mask:0xf bound_ctrl:1
	v_fmac_f32_dpp v205, v205, v167 row_shr:8 row_mask:0xf bank_mask:0xf bound_ctrl:1
	v_fmac_f32_dpp v206, v206, v168 row_shr:8 row_mask:0xf bank_mask:0xf bound_ctrl:1
	v_fmac_f32_dpp v207, v207, v169 row_shr:8 row_mask:0xf bank_mask:0xf bound_ctrl:1
	v_mul_f32_dpp v166, v166, v166 row_shr:8 row_mask:0xf bank_mask:0xf
	v_mul_f32_dpp v167, v167, v167 row_shr:8 row_mask:0xf bank_mask:0xf
	v_mul_f32_dpp v168, v168, v168 row_shr:8 row_mask:0xf bank_mask:0xf
	v_mul_f32_dpp v169, v169, v169 row_shr:8 row_mask:0xf bank_mask:0xf
	v_fma_f32 v208, v166, v20, v204
	v_fma_f32 v209, v167, v21, v205
	v_fma_f32 v210, v168, v22, v206
	v_fma_f32 v211, v169, v23, v207
	v_mov_b32_dpp v20, v208 row_newbcast:15 row_mask:0xf bank_mask:0xf
	v_mov_b32_dpp v21, v209 row_newbcast:15 row_mask:0xf bank_mask:0xf
	v_mov_b32_dpp v22, v210 row_newbcast:15 row_mask:0xf bank_mask:0xf
	v_mov_b32_dpp v23, v211 row_newbcast:15 row_mask:0xf bank_mask:0xf
	s_waitcnt vmcnt(24)
	v_lshlrev_b32_e32 v212, 16, v34
	v_and_b32_e32 v213, 0xffff0000, v34
	v_lshlrev_b32_e32 v214, 16, v35
	v_and_b32_e32 v215, 0xffff0000, v35
	v_pk_mul_f32 v[216:217], v[212:213], v[212:213]
	v_pk_mul_f32 v[218:219], v[214:215], v[214:215]
	v_pk_fma_f32 v[216:217], v[216:217], v[36:37], v[36:37] op_sel:[0,0,1] op_sel_hi:[1,0,1]
	v_pk_fma_f32 v[218:219], v[218:219], v[36:37], v[36:37] op_sel:[0,0,1] op_sel_hi:[1,0,1]
	v_pk_mul_f32 v[216:217], v[212:213], v[216:217]
	v_pk_mul_f32 v[218:219], v[214:215], v[218:219]
	v_exp_f32_e32 v216, v216
	v_exp_f32_e32 v217, v217
	v_exp_f32_e32 v218, v218
	v_exp_f32_e32 v219, v219
	v_pk_add_f32 v[216:217], v[216:217], 1.0 op_sel_hi:[1,0]
	v_pk_add_f32 v[218:219], v[218:219], 1.0 op_sel_hi:[1,0]
	v_rcp_f32_e32 v216, v216
	v_rcp_f32_e32 v217, v217
	v_rcp_f32_e32 v218, v218
	v_rcp_f32_e32 v219, v219
	v_pk_mul_f32 v[216:217], v[212:213], v[216:217]
	v_pk_mul_f32 v[218:219], v[214:215], v[218:219]
	v_pk_mul_f32 v[216:217], v[216:217], v[208:209]
	v_pk_mul_f32 v[218:219], v[218:219], v[210:211]
	v_cvt_pk_bf16_f32 v242, v216, v217
	v_cvt_pk_bf16_f32 v243, v218, v219
	global_store_dwordx2 v236, v[242:243], s[100:101] offset:160
	s_waitcnt lgkmcnt(0)
	s_waitcnt vmcnt(6)
	v_mov_b32_e32 v66, v82
	v_mov_b32_e32 v67, v83
	v_mov_b32_e32 v68, v84
	v_mov_b32_e32 v69, v85
	v_mov_b32_e32 v70, v86
	v_mov_b32_e32 v71, v87
	v_mov_b32_e32 v72, v88
	v_mov_b32_e32 v73, v89
	v_mov_b32_e32 v74, v90
	v_mov_b32_e32 v75, v91
	v_mov_b32_e32 v76, v92
	v_mov_b32_e32 v77, v93
	v_mov_b32_e32 v78, v94
	v_mov_b32_e32 v79, v95
	v_mov_b32_e32 v80, v96
	v_mov_b32_e32 v81, v97
	s_add_u32 s6, s6, 0x18000
	s_addc_u32 s7, s7, 0
	s_add_u32 s100, s100, 0xc000
	s_addc_u32 s101, s101, 0
	s_add_i32 s64, s64, 1
	s_cmp_lt_u32 s64, 3
	s_cbranch_scc1 .Lscan2_sub
	s_add_i32 s23, s23, s42
